# attention A: P.V of tile t-1 issued behind the QK MFMAs of tile t (5-slot ring, separate P buffer), exps of tile t between those MFMAs
# baseline (speedup 1.0000x reference)
.LBB0_342:
	s_and_b64 s[24:25], s[36:37], exec
	s_cselect_b32 s54, s44, s45
	s_ashr_i32 s55, s54, 6
	s_sub_i32 s4, 7, s55
	s_lshl_b32 s24, s4, 8
	s_add_i32 s24, s24, s40
	s_lshl_b32 s53, s4, 2
	s_lshl_b32 s4, s54, 9
	s_add_i32 s52, s53, s41
	s_and_b32 s26, s4, 0x7800
	s_ashr_i32 s4, s24, 31
	s_add_u32 s57, s24, s26
	s_addc_u32 s58, s4, 0
	s_lshl_b32 s4, s54, 7
	s_mul_i32 s24, s58, 0x1800
	s_mul_hi_u32 s25, s57, 0x1800
	s_and_b32 s4, s4, 0x180
	s_add_i32 s25, s25, s24
	s_mul_i32 s24, s57, 0x1800
	s_add_u32 s24, s10, s24
	s_addc_u32 s25, s11, s25
	s_lshl_b32 s4, s4, 1
	s_add_u32 s24, s24, s4
	s_addc_u32 s25, s25, 0
	v_lshl_add_u64 v[2:3], s[24:25], 0, v[132:133]
	v_lshl_add_u64 v[128:129], v[2:3], 0, v[134:135]
	global_load_dwordx4 v[112:115], v[128:129], off
	global_load_dwordx4 v[116:119], v[128:129], off offset:32
	global_load_dwordx4 v[120:123], v[128:129], off offset:64
	global_load_dwordx4 v[124:127], v[128:129], off offset:96
	s_mul_i32 s56, s26, 0x1800
	s_add_u32 s25, s10, s56
	s_addc_u32 s26, s11, 0
	s_add_u32 s30, s25, s4
	s_addc_u32 s31, s26, 0
	s_add_u32 s28, s30, 0x400
	s_addc_u32 s29, s31, 0
	v_readfirstlane_b32 s24, v215
	s_add_u32 s26, s30, 0x800
	s_addc_u32 s27, s31, 0
	s_lshr_b32 s24, s24, 6
	s_lshl_b32 s25, s24, 3
	v_or_b32_e32 v0, s25, v172
	v_or_b32_e32 v2, s25, v184
	v_lshrrev_b32_e32 v4, 1, v0
	v_mul_lo_u32 v6, v2, s42
	v_xor_b32_e32 v7, v4, v215
	v_or_b32_e32 v2, v6, v194
	v_add_u32_e32 v4, v6, v195
	v_lshlrev_b32_e32 v6, 3, v7
	v_mul_lo_u32 v0, v0, s42
	v_and_b32_e32 v6, 56, v6
	s_lshl_b32 s59, s24, 10
	v_or_b32_e32 v0, v6, v0
	v_mov_b32_e32 v3, v1
	s_lshl_b32 s60, s24, 11
	s_add_i32 s38, s59, 0
	v_lshl_add_u64 v[12:13], v[0:1], 1, s[30:31]
	s_add_i32 s25, s60, 0
	v_lshl_add_u64 v[8:9], v[2:3], 1, s[30:31]
	v_lshl_add_u64 v[12:13], v[12:13], 0, s[6:7]
	s_mov_b32 m0, s38
	v_mov_b32_e32 v5, v1
	v_lshl_add_u64 v[8:9], v[8:9], 0, s[12:13]
	v_lshl_add_u64 v[10:11], v[4:5], 1, s[26:27]
	s_add_i32 s53, s53, 4
	s_barrier
	global_load_lds_dwordx4 v[12:13], off
	s_add_i32 m0, s25, 0x2000
	s_nop 0
	global_load_lds_dwordx4 v[8:9], off
	s_add_i32 m0, s25, 0x2400
	s_cmp_lt_i32 s55, 8
	global_load_lds_dwordx4 v[10:11], off
	s_cselect_b64 s[34:35], -1, 0
	s_cmp_gt_i32 s55, 7
	s_cbranch_scc1 .LBB0_359
	s_add_u32 s62, s26, 0x60000
	v_lshl_add_u64 v[12:13], v[0:1], 1, s[28:29]
	s_addc_u32 s63, s27, 0
	v_lshlrev_b64 v[2:3], 1, v[2:3]
	v_lshl_add_u64 v[14:15], v[12:13], 0, s[14:15]
	s_add_i32 m0, s38, 0x6000
	v_lshl_add_u64 v[10:11], s[62:63], 0, v[2:3]
	global_load_lds_dwordx4 v[14:15], off
	s_add_i32 m0, s25, 0x8000
	v_lshlrev_b64 v[4:5], 1, v[4:5]
	global_load_lds_dwordx4 v[10:11], off
	s_add_i32 m0, s25, 0x8400
	v_lshl_add_u64 v[8:9], s[62:63], 0, v[4:5]
	s_add_u32 s62, s26, 0xc0000
	global_load_lds_dwordx4 v[8:9], off
	s_addc_u32 s63, s27, 0
	v_lshl_add_u64 v[8:9], v[12:13], 0, s[16:17]
	s_add_i32 m0, s38, 0xc000
	v_lshl_add_u64 v[2:3], s[62:63], 0, v[2:3]
	global_load_lds_dwordx4 v[8:9], off
	s_add_i32 m0, s25, 0xe000
	v_lshl_add_u64 v[4:5], s[62:63], 0, v[4:5]
	global_load_lds_dwordx4 v[2:3], off
	s_add_i32 m0, s25, 0xe400
	s_mul_i32 s38, s24, 0x6000
	global_load_lds_dwordx4 v[4:5], off
	s_and_b32 s24, s54, 3
	s_lshl_b32 s61, s55, 2
	v_add_u32_e32 v0, s38, v196
	s_lshl_b32 s24, s24, 8
	v_lshl_add_u64 v[130:131], v[0:1], 1, v[138:139]
	s_add_u32 s24, s56, s24
	v_add_u32_e32 v0, s38, v197
	s_addc_u32 s25, 0, 0
	v_lshl_add_u64 v[146:147], v[0:1], 1, v[138:139]
	v_add3_u32 v0, v188, s38, v6
	v_mov_b32_e32 v14, v1
	v_mov_b32_e32 v15, v1
	s_add_u32 s24, s50, s24
	v_lshl_add_u64 v[148:149], v[0:1], 1, v[140:141]
	v_mov_b32_e32 v0, v1
	v_mov_b32_e32 v2, v1
	v_mov_b32_e32 v3, v1
	v_mov_b32_e32 v4, v1
	v_mov_b32_e32 v5, v1
	v_mov_b32_e32 v6, v1
	v_mov_b32_e32 v7, v1
	v_mov_b32_e32 v8, v1
	v_mov_b32_e32 v9, v1
	v_mov_b32_e32 v10, v1
	v_mov_b32_e32 v11, v1
	v_mov_b32_e32 v12, v1
	v_mov_b32_e32 v13, v1
	v_mov_b64_e32 v[30:31], v[14:15]
	v_mov_b64_e32 v[46:47], v[14:15]
	v_mov_b64_e32 v[62:63], v[14:15]
	v_mov_b64_e32 v[78:79], v[14:15]
	s_addc_u32 s25, s51, s25
	s_sub_i32 s62, 31, s61
	s_mov_b32 s63, 0
	s_mov_b32 s98, 0
	s_mov_b32 s99, 0
	v_mov_b32_e32 v150, 0
	v_mov_b32_e32 v151, 0xf149f2ca
	v_mov_b64_e32 v[28:29], v[12:13]
	v_mov_b64_e32 v[26:27], v[10:11]
	v_mov_b64_e32 v[24:25], v[8:9]
	v_mov_b64_e32 v[22:23], v[6:7]
	v_mov_b64_e32 v[20:21], v[4:5]
	v_mov_b64_e32 v[18:19], v[2:3]
	v_mov_b64_e32 v[16:17], v[0:1]
	v_mov_b64_e32 v[44:45], v[12:13]
	v_mov_b64_e32 v[42:43], v[10:11]
	v_mov_b64_e32 v[40:41], v[8:9]
	v_mov_b64_e32 v[38:39], v[6:7]
	v_mov_b64_e32 v[36:37], v[4:5]
	v_mov_b64_e32 v[34:35], v[2:3]
	v_mov_b64_e32 v[32:33], v[0:1]
	v_mov_b64_e32 v[60:61], v[12:13]
	v_mov_b64_e32 v[58:59], v[10:11]
	v_mov_b64_e32 v[56:57], v[8:9]
	v_mov_b64_e32 v[54:55], v[6:7]
	v_mov_b64_e32 v[52:53], v[4:5]
	v_mov_b64_e32 v[50:51], v[2:3]
	v_mov_b64_e32 v[48:49], v[0:1]
	v_mov_b64_e32 v[76:77], v[12:13]
	v_mov_b64_e32 v[74:75], v[10:11]
	v_mov_b64_e32 v[72:73], v[8:9]
	v_mov_b64_e32 v[70:71], v[6:7]
	v_mov_b64_e32 v[68:69], v[4:5]
	v_mov_b64_e32 v[66:67], v[2:3]
	v_mov_b64_e32 v[64:65], v[0:1]
	s_branch .LBB0_346

.LBB0_345:
	s_add_i32 s63, s63, 1
	s_add_i32 s98, s98, 1
	s_cmp_eq_u32 s98, 5
	s_cselect_b32 s98, 0, s98
	s_add_i32 s38, s61, s63
	s_add_u32 s24, s24, 0x60000
	s_addc_u32 s25, s25, 0
	s_add_i32 s62, s62, -1
	s_cmp_lg_u32 s38, 32
	s_cbranch_scc0 .Lq1_exit

.LBB0_353:
	s_waitcnt lgkmcnt(0)
	s_barrier
	s_add_i32 s38, s63, 3
	s_cmp_ge_i32 s38, s53
	s_cbranch_scc1 .LBB0_355
	s_add_i32 s38, s98, 3
	s_add_i32 s101, s98, -2
	s_cmp_gt_u32 s38, 4
	s_cselect_b32 s38, s101, s38
	s_mulk_i32 s38, 0x6000
	s_add_i32 s38, s38, 0
	s_add_i32 m0, s38, s59
	s_add_i32 s38, s38, s60
	global_load_lds_dwordx4 v148, s[24:25]
	s_add_i32 m0, s38, 0x2000
	s_nop 0
	global_load_lds_dwordx4 v130, s[24:25]
	s_add_i32 m0, s38, 0x2400
	s_nop 0
	global_load_lds_dwordx4 v146, s[24:25]
.LBB0_355:
	s_branch .Lq1_body
.LBB0_358:
	s_branch .LBB0_349
.Lq1_body:
	s_cmp_gt_i32 s63, s52
	s_cbranch_scc0 .Lq1_work
	s_cmp_eq_u32 s99, 0
	s_cbranch_scc1 .LBB0_345
	v_add3_u32 v248, s100, v199, v187
	v_add3_u32 v249, s100, v199, v190
	v_add3_u32 v250, s100, v199, v191
	v_add3_u32 v251, s100, v199, v192
	ds_read_b64_tr_b16 v[2:3], v248 offset:8192
	ds_read_b64_tr_b16 v[4:5], v248 offset:10240
	ds_read_b64_tr_b16 v[6:7], v249 offset:8192
	ds_read_b64_tr_b16 v[8:9], v249 offset:10240
	ds_read_b64_tr_b16 v[10:11], v250 offset:8192
	ds_read_b64_tr_b16 v[12:13], v250 offset:10240
	ds_read_b64_tr_b16 v[244:245], v251 offset:8192
	ds_read_b64_tr_b16 v[246:247], v251 offset:10240
	s_waitcnt lgkmcnt(6)
	v_mfma_f32_32x32x16_bf16 v[64:79], v[2:5], v[200:203], v[64:79]
	ds_read_b64_tr_b16 v[156:157], v248 offset:12288
	ds_read_b64_tr_b16 v[158:159], v248 offset:14336
	ds_read_b64_tr_b16 v[160:161], v249 offset:12288
	ds_read_b64_tr_b16 v[162:163], v249 offset:14336
	ds_read_b64_tr_b16 v[252:253], v250 offset:12288
	ds_read_b64_tr_b16 v[254:255], v250 offset:14336
	ds_read_b64_tr_b16 v[216:217], v251 offset:12288
	ds_read_b64_tr_b16 v[218:219], v251 offset:14336
	s_waitcnt lgkmcnt(12)
	v_mfma_f32_32x32x16_bf16 v[48:63], v[6:9], v[200:203], v[48:63]
	s_waitcnt lgkmcnt(10)
	v_mfma_f32_32x32x16_bf16 v[32:47], v[10:13], v[200:203], v[32:47]
	s_waitcnt lgkmcnt(8)
	v_mfma_f32_32x32x16_bf16 v[16:31], v[244:247], v[200:203], v[16:31]
	s_waitcnt lgkmcnt(6)
	v_mfma_f32_32x32x16_bf16 v[64:79], v[156:159], v[204:207], v[64:79]
	ds_read_b64_tr_b16 v[2:3], v248 offset:16384
	ds_read_b64_tr_b16 v[4:5], v248 offset:18432
	ds_read_b64_tr_b16 v[6:7], v249 offset:16384
	ds_read_b64_tr_b16 v[8:9], v249 offset:18432
	ds_read_b64_tr_b16 v[10:11], v250 offset:16384
	ds_read_b64_tr_b16 v[12:13], v250 offset:18432
	ds_read_b64_tr_b16 v[244:245], v251 offset:16384
	ds_read_b64_tr_b16 v[246:247], v251 offset:18432
	s_waitcnt lgkmcnt(12)
	v_mfma_f32_32x32x16_bf16 v[48:63], v[160:163], v[204:207], v[48:63]
	s_waitcnt lgkmcnt(10)
	v_mfma_f32_32x32x16_bf16 v[32:47], v[252:255], v[204:207], v[32:47]
	s_waitcnt lgkmcnt(8)
	v_mfma_f32_32x32x16_bf16 v[16:31], v[216:219], v[204:207], v[16:31]
	s_waitcnt lgkmcnt(6)
	v_mfma_f32_32x32x16_bf16 v[64:79], v[2:5], v[208:211], v[64:79]
	ds_read_b64_tr_b16 v[156:157], v248 offset:20480
	ds_read_b64_tr_b16 v[158:159], v248 offset:22528
	ds_read_b64_tr_b16 v[160:161], v249 offset:20480
	ds_read_b64_tr_b16 v[162:163], v249 offset:22528
	ds_read_b64_tr_b16 v[252:253], v250 offset:20480
	ds_read_b64_tr_b16 v[254:255], v250 offset:22528
	ds_read_b64_tr_b16 v[216:217], v251 offset:20480
	ds_read_b64_tr_b16 v[218:219], v251 offset:22528
	s_waitcnt lgkmcnt(12)
	v_mfma_f32_32x32x16_bf16 v[48:63], v[6:9], v[208:211], v[48:63]
	s_waitcnt lgkmcnt(10)
	v_mfma_f32_32x32x16_bf16 v[32:47], v[10:13], v[208:211], v[32:47]
	s_waitcnt lgkmcnt(8)
	v_mfma_f32_32x32x16_bf16 v[16:31], v[244:247], v[208:211], v[16:31]
	s_waitcnt lgkmcnt(6)
	v_mfma_f32_32x32x16_bf16 v[64:79], v[156:159], v[220:223], v[64:79]
	s_waitcnt lgkmcnt(4)
	v_mfma_f32_32x32x16_bf16 v[48:63], v[160:163], v[220:223], v[48:63]
	s_waitcnt lgkmcnt(2)
	v_mfma_f32_32x32x16_bf16 v[32:47], v[252:255], v[220:223], v[32:47]
	s_waitcnt lgkmcnt(0)
	v_mfma_f32_32x32x16_bf16 v[16:31], v[216:219], v[220:223], v[16:31]
	s_mov_b32 s99, 0
	s_branch .LBB0_345
.Lq1_work:
	s_mov_b32 s38, s98
	s_mulk_i32 s38, 0x6000
	s_add_i32 s38, s38, 0
	v_add3_u32 v14, s38, v174, v173
	v_add3_u32 v15, s38, v174, v177
	ds_read_b128 v[2:5], v14
	ds_read_b128 v[6:9], v14 offset:4096
	ds_read_b128 v[10:13], v15
	ds_read_b128 v[152:155], v15 offset:4096
	v_add3_u32 v14, s38, v174, v179
	v_add3_u32 v15, s38, v174, v180
	ds_read_b128 v[156:159], v14
	ds_read_b128 v[160:163], v14 offset:4096
	ds_read_b128 v[244:247], v15
	ds_read_b128 v[248:251], v15 offset:4096
	s_waitcnt lgkmcnt(6)
	v_mfma_f32_32x32x16_bf16 v[96:111], v[2:5], v[112:115], 0
	v_mfma_f32_32x32x16_bf16 v[80:95], v[6:9], v[112:115], 0
	s_waitcnt lgkmcnt(4)
	v_mfma_f32_32x32x16_bf16 v[96:111], v[10:13], v[116:119], v[96:111]
	v_mfma_f32_32x32x16_bf16 v[80:95], v[152:155], v[116:119], v[80:95]
	s_waitcnt lgkmcnt(2)
	v_mfma_f32_32x32x16_bf16 v[96:111], v[156:159], v[120:123], v[96:111]
	v_mfma_f32_32x32x16_bf16 v[80:95], v[160:163], v[120:123], v[80:95]
	s_waitcnt lgkmcnt(0)
	v_mfma_f32_32x32x16_bf16 v[80:95], v[248:251], v[124:127], v[80:95]
	v_mfma_f32_32x32x16_bf16 v[96:111], v[244:247], v[124:127], v[96:111]
	s_cmp_eq_u32 s99, 0
	s_cbranch_scc1 .Lq1_first
	v_add3_u32 v248, s100, v199, v187
	v_add3_u32 v249, s100, v199, v190
	v_add3_u32 v250, s100, v199, v191
	v_add3_u32 v251, s100, v199, v192
	ds_read_b64_tr_b16 v[2:3], v248 offset:8192
	ds_read_b64_tr_b16 v[4:5], v248 offset:10240
	ds_read_b64_tr_b16 v[6:7], v249 offset:8192
	ds_read_b64_tr_b16 v[8:9], v249 offset:10240
	ds_read_b64_tr_b16 v[10:11], v250 offset:8192
	ds_read_b64_tr_b16 v[12:13], v250 offset:10240
	ds_read_b64_tr_b16 v[244:245], v251 offset:8192
	ds_read_b64_tr_b16 v[246:247], v251 offset:10240
	s_waitcnt lgkmcnt(6)
	v_mfma_f32_32x32x16_bf16 v[64:79], v[2:5], v[200:203], v[64:79]
	ds_read_b64_tr_b16 v[156:157], v248 offset:12288
	ds_read_b64_tr_b16 v[158:159], v248 offset:14336
	ds_read_b64_tr_b16 v[160:161], v249 offset:12288
	ds_read_b64_tr_b16 v[162:163], v249 offset:14336
	ds_read_b64_tr_b16 v[252:253], v250 offset:12288
	ds_read_b64_tr_b16 v[254:255], v250 offset:14336
	ds_read_b64_tr_b16 v[216:217], v251 offset:12288
	ds_read_b64_tr_b16 v[218:219], v251 offset:14336
	s_waitcnt lgkmcnt(12)
	v_mfma_f32_32x32x16_bf16 v[48:63], v[6:9], v[200:203], v[48:63]
	s_waitcnt lgkmcnt(10)
	v_mfma_f32_32x32x16_bf16 v[32:47], v[10:13], v[200:203], v[32:47]
	s_waitcnt lgkmcnt(8)
	v_mfma_f32_32x32x16_bf16 v[16:31], v[244:247], v[200:203], v[16:31]
	v_max3_f32 v0, v80, v81, v82
	v_max3_f32 v2, v83, v84, v85
	v_max3_f32 v3, v86, v87, v88
	v_max3_f32 v4, v89, v90, v91
	v_max3_f32 v0, v0, v92, v93
	v_max3_f32 v2, v2, v94, v95
	v_max3_f32 v3, v3, v96, v97
	v_max3_f32 v4, v4, v98, v99
	v_max3_f32 v0, v0, v100, v101
	v_max3_f32 v2, v2, v102, v103
	v_max3_f32 v3, v3, v104, v105
	v_max3_f32 v4, v4, v106, v107
	v_max3_f32 v0, v0, v108, v109
	v_max3_f32 v2, v2, v110, v111
	v_max3_f32 v0, v0, v3, v4
	v_max_f32_e32 v0, v0, v2
	v_mul_f32_e32 v0, 0x3e38aa3b, v0
	v_mov_b32_e32 v2, v0
	s_nop 1
	v_permlane32_swap_b32_e32 v0, v2
	v_max_f32_e32 v0, v0, v2
	v_add_f32_e32 v2, 0x41000000, v151
	v_cmp_gt_f32_e32 vcc, v0, v2
	s_cbranch_vccz .Lq1_fast
	s_waitcnt lgkmcnt(6)
	v_mfma_f32_32x32x16_bf16 v[64:79], v[156:159], v[204:207], v[64:79]
	ds_read_b64_tr_b16 v[2:3], v248 offset:16384
	ds_read_b64_tr_b16 v[4:5], v248 offset:18432
	ds_read_b64_tr_b16 v[6:7], v249 offset:16384
	ds_read_b64_tr_b16 v[8:9], v249 offset:18432
	ds_read_b64_tr_b16 v[10:11], v250 offset:16384
	ds_read_b64_tr_b16 v[12:13], v250 offset:18432
	ds_read_b64_tr_b16 v[244:245], v251 offset:16384
	ds_read_b64_tr_b16 v[246:247], v251 offset:18432
	s_waitcnt lgkmcnt(12)
	v_mfma_f32_32x32x16_bf16 v[48:63], v[160:163], v[204:207], v[48:63]
	s_waitcnt lgkmcnt(10)
	v_mfma_f32_32x32x16_bf16 v[32:47], v[252:255], v[204:207], v[32:47]
	s_waitcnt lgkmcnt(8)
	v_mfma_f32_32x32x16_bf16 v[16:31], v[216:219], v[204:207], v[16:31]
	s_waitcnt lgkmcnt(6)
	v_mfma_f32_32x32x16_bf16 v[64:79], v[2:5], v[208:211], v[64:79]
	ds_read_b64_tr_b16 v[156:157], v248 offset:20480
	ds_read_b64_tr_b16 v[158:159], v248 offset:22528
	ds_read_b64_tr_b16 v[160:161], v249 offset:20480
	ds_read_b64_tr_b16 v[162:163], v249 offset:22528
	ds_read_b64_tr_b16 v[252:253], v250 offset:20480
	ds_read_b64_tr_b16 v[254:255], v250 offset:22528
	ds_read_b64_tr_b16 v[216:217], v251 offset:20480
	ds_read_b64_tr_b16 v[218:219], v251 offset:22528
	s_waitcnt lgkmcnt(12)
	v_mfma_f32_32x32x16_bf16 v[48:63], v[6:9], v[208:211], v[48:63]
	s_waitcnt lgkmcnt(10)
	v_mfma_f32_32x32x16_bf16 v[32:47], v[10:13], v[208:211], v[32:47]
	s_waitcnt lgkmcnt(8)
	v_mfma_f32_32x32x16_bf16 v[16:31], v[244:247], v[208:211], v[16:31]
	s_waitcnt lgkmcnt(6)
	v_mfma_f32_32x32x16_bf16 v[64:79], v[156:159], v[220:223], v[64:79]
	s_waitcnt lgkmcnt(4)
	v_mfma_f32_32x32x16_bf16 v[48:63], v[160:163], v[220:223], v[48:63]
	s_waitcnt lgkmcnt(2)
	v_mfma_f32_32x32x16_bf16 v[32:47], v[252:255], v[220:223], v[32:47]
	s_waitcnt lgkmcnt(0)
	v_mfma_f32_32x32x16_bf16 v[16:31], v[216:219], v[220:223], v[16:31]
	s_nop 7
	s_nop 7
	v_max_f32_e32 v0, v0, v0
	v_max_f32_e32 v2, v151, v151
	v_max_f32_e32 v2, v2, v0
	v_sub_f32_e32 v0, v151, v2
	v_exp_f32_e32 v0, v0
	v_mov_b32_e32 v151, v2
	v_pk_mul_f32 v[78:79], v[0:1], v[78:79] op_sel_hi:[0,1]
	v_pk_mul_f32 v[76:77], v[0:1], v[76:77] op_sel_hi:[0,1]
	v_pk_mul_f32 v[74:75], v[0:1], v[74:75] op_sel_hi:[0,1]
	v_pk_mul_f32 v[72:73], v[0:1], v[72:73] op_sel_hi:[0,1]
	v_pk_mul_f32 v[70:71], v[0:1], v[70:71] op_sel_hi:[0,1]
	v_pk_mul_f32 v[68:69], v[0:1], v[68:69] op_sel_hi:[0,1]
	v_pk_mul_f32 v[66:67], v[0:1], v[66:67] op_sel_hi:[0,1]
	v_pk_mul_f32 v[64:65], v[0:1], v[64:65] op_sel_hi:[0,1]
	v_pk_mul_f32 v[62:63], v[0:1], v[62:63] op_sel_hi:[0,1]
	v_pk_mul_f32 v[60:61], v[0:1], v[60:61] op_sel_hi:[0,1]
	v_pk_mul_f32 v[58:59], v[0:1], v[58:59] op_sel_hi:[0,1]
	v_pk_mul_f32 v[56:57], v[0:1], v[56:57] op_sel_hi:[0,1]
	v_pk_mul_f32 v[54:55], v[0:1], v[54:55] op_sel_hi:[0,1]
	v_pk_mul_f32 v[52:53], v[0:1], v[52:53] op_sel_hi:[0,1]
	v_pk_mul_f32 v[50:51], v[0:1], v[50:51] op_sel_hi:[0,1]
	v_pk_mul_f32 v[48:49], v[0:1], v[48:49] op_sel_hi:[0,1]
	v_pk_mul_f32 v[46:47], v[0:1], v[46:47] op_sel_hi:[0,1]
	v_pk_mul_f32 v[44:45], v[0:1], v[44:45] op_sel_hi:[0,1]
	v_pk_mul_f32 v[42:43], v[0:1], v[42:43] op_sel_hi:[0,1]
	v_pk_mul_f32 v[40:41], v[0:1], v[40:41] op_sel_hi:[0,1]
	v_pk_mul_f32 v[38:39], v[0:1], v[38:39] op_sel_hi:[0,1]
	v_pk_mul_f32 v[36:37], v[0:1], v[36:37] op_sel_hi:[0,1]
	v_pk_mul_f32 v[34:35], v[0:1], v[34:35] op_sel_hi:[0,1]
	v_pk_mul_f32 v[32:33], v[0:1], v[32:33] op_sel_hi:[0,1]
	v_pk_mul_f32 v[30:31], v[0:1], v[30:31] op_sel_hi:[0,1]
	v_pk_mul_f32 v[28:29], v[0:1], v[28:29] op_sel_hi:[0,1]
	v_pk_mul_f32 v[26:27], v[0:1], v[26:27] op_sel_hi:[0,1]
	v_pk_mul_f32 v[24:25], v[0:1], v[24:25] op_sel_hi:[0,1]
	v_pk_mul_f32 v[22:23], v[0:1], v[22:23] op_sel_hi:[0,1]
	v_pk_mul_f32 v[20:21], v[0:1], v[20:21] op_sel_hi:[0,1]
	v_pk_mul_f32 v[18:19], v[0:1], v[18:19] op_sel_hi:[0,1]
	v_pk_mul_f32 v[16:17], v[0:1], v[16:17] op_sel_hi:[0,1]
	v_mul_f32_e32 v150, v150, v0
	v_fma_f32 v96, v96, s43, -v151
	v_exp_f32_e32 v96, v96
	v_fma_f32 v97, v97, s43, -v151
	v_exp_f32_e32 v97, v97
	v_fma_f32 v98, v98, s43, -v151
	v_exp_f32_e32 v98, v98
	v_fma_f32 v99, v99, s43, -v151
	v_exp_f32_e32 v99, v99
	v_fma_f32 v100, v100, s43, -v151
	v_exp_f32_e32 v100, v100
	v_fma_f32 v101, v101, s43, -v151
	v_exp_f32_e32 v101, v101
	v_fma_f32 v102, v102, s43, -v151
	v_exp_f32_e32 v102, v102
	v_fma_f32 v103, v103, s43, -v151
	v_exp_f32_e32 v103, v103
	v_add_f32_e32 v0, v96, v97
	v_add_f32_e32 v14, v98, v99
	v_add_f32_e32 v15, v100, v101
	v_add_f32_e32 v0, v0, v102
	v_add_f32_e32 v14, v14, v103
	v_cvt_pk_bf16_f32 v200, v96, v97
	v_cvt_pk_bf16_f32 v201, v98, v99
	v_cvt_pk_bf16_f32 v202, v100, v101
	v_cvt_pk_bf16_f32 v203, v102, v103
	v_fma_f32 v104, v104, s43, -v151
	v_exp_f32_e32 v104, v104
	v_fma_f32 v105, v105, s43, -v151
	v_exp_f32_e32 v105, v105
	v_fma_f32 v106, v106, s43, -v151
	v_exp_f32_e32 v106, v106
	v_fma_f32 v107, v107, s43, -v151
	v_exp_f32_e32 v107, v107
	v_fma_f32 v108, v108, s43, -v151
	v_exp_f32_e32 v108, v108
	v_fma_f32 v109, v109, s43, -v151
	v_exp_f32_e32 v109, v109
	v_fma_f32 v110, v110, s43, -v151
	v_exp_f32_e32 v110, v110
	v_fma_f32 v111, v111, s43, -v151
	v_exp_f32_e32 v111, v111
	v_add_f32_e32 v0, v0, v104
	v_add_f32_e32 v14, v14, v105
	v_add_f32_e32 v15, v15, v106
	v_add_f32_e32 v0, v0, v107
	v_add_f32_e32 v14, v14, v108
	v_add_f32_e32 v15, v15, v109
	v_add_f32_e32 v0, v0, v110
	v_add_f32_e32 v14, v14, v111
	v_cvt_pk_bf16_f32 v204, v104, v105
	v_cvt_pk_bf16_f32 v205, v106, v107
	v_cvt_pk_bf16_f32 v206, v108, v109
	v_cvt_pk_bf16_f32 v207, v110, v111
	v_fma_f32 v80, v80, s43, -v151
	v_exp_f32_e32 v80, v80
	v_fma_f32 v81, v81, s43, -v151
	v_exp_f32_e32 v81, v81
	v_fma_f32 v82, v82, s43, -v151
	v_exp_f32_e32 v82, v82
	v_fma_f32 v83, v83, s43, -v151
	v_exp_f32_e32 v83, v83
	v_fma_f32 v84, v84, s43, -v151
	v_exp_f32_e32 v84, v84
	v_fma_f32 v85, v85, s43, -v151
	v_exp_f32_e32 v85, v85
	v_fma_f32 v86, v86, s43, -v151
	v_exp_f32_e32 v86, v86
	v_fma_f32 v87, v87, s43, -v151
	v_exp_f32_e32 v87, v87
	v_add_f32_e32 v0, v0, v80
	v_add_f32_e32 v14, v14, v81
	v_add_f32_e32 v15, v15, v82
	v_add_f32_e32 v0, v0, v83
	v_add_f32_e32 v14, v14, v84
	v_add_f32_e32 v15, v15, v85
	v_add_f32_e32 v0, v0, v86
	v_add_f32_e32 v14, v14, v87
	v_cvt_pk_bf16_f32 v208, v80, v81
	v_cvt_pk_bf16_f32 v209, v82, v83
	v_cvt_pk_bf16_f32 v210, v84, v85
	v_cvt_pk_bf16_f32 v211, v86, v87
	v_fma_f32 v88, v88, s43, -v151
	v_exp_f32_e32 v88, v88
	v_fma_f32 v89, v89, s43, -v151
	v_exp_f32_e32 v89, v89
	v_fma_f32 v90, v90, s43, -v151
	v_exp_f32_e32 v90, v90
	v_fma_f32 v91, v91, s43, -v151
	v_exp_f32_e32 v91, v91
	v_fma_f32 v92, v92, s43, -v151
	v_exp_f32_e32 v92, v92
	v_fma_f32 v93, v93, s43, -v151
	v_exp_f32_e32 v93, v93
	v_fma_f32 v94, v94, s43, -v151
	v_exp_f32_e32 v94, v94
	v_fma_f32 v95, v95, s43, -v151
	v_exp_f32_e32 v95, v95
	v_add_f32_e32 v0, v0, v88
	v_add_f32_e32 v14, v14, v89
	v_add_f32_e32 v15, v15, v90
	v_add_f32_e32 v0, v0, v91
	v_add_f32_e32 v14, v14, v92
	v_add_f32_e32 v15, v15, v93
	v_add_f32_e32 v0, v0, v94
	v_add_f32_e32 v14, v14, v95
	v_cvt_pk_bf16_f32 v220, v88, v89
	v_cvt_pk_bf16_f32 v221, v90, v91
	v_cvt_pk_bf16_f32 v222, v92, v93
	v_cvt_pk_bf16_f32 v223, v94, v95
	v_add_f32_e32 v0, v0, v14
	v_add_f32_e32 v150, v150, v15
	v_add_f32_e32 v150, v150, v0
	s_mov_b32 s100, s38
	s_branch .LBB0_345
.Lq1_fast:
	s_waitcnt lgkmcnt(6)
	v_mfma_f32_32x32x16_bf16 v[64:79], v[156:159], v[204:207], v[64:79]
	ds_read_b64_tr_b16 v[2:3], v248 offset:16384
	ds_read_b64_tr_b16 v[4:5], v248 offset:18432
	ds_read_b64_tr_b16 v[6:7], v249 offset:16384
	ds_read_b64_tr_b16 v[8:9], v249 offset:18432
	ds_read_b64_tr_b16 v[10:11], v250 offset:16384
	ds_read_b64_tr_b16 v[12:13], v250 offset:18432
	ds_read_b64_tr_b16 v[244:245], v251 offset:16384
	ds_read_b64_tr_b16 v[246:247], v251 offset:18432
	v_fma_f32 v96, v96, s43, -v151
	v_exp_f32_e32 v96, v96
	v_fma_f32 v97, v97, s43, -v151
	v_exp_f32_e32 v97, v97
	v_fma_f32 v98, v98, s43, -v151
	v_exp_f32_e32 v98, v98
	v_fma_f32 v99, v99, s43, -v151
	s_waitcnt lgkmcnt(12)
	v_mfma_f32_32x32x16_bf16 v[48:63], v[160:163], v[204:207], v[48:63]
	v_exp_f32_e32 v99, v99
	v_fma_f32 v100, v100, s43, -v151
	v_exp_f32_e32 v100, v100
	v_fma_f32 v101, v101, s43, -v151
	v_exp_f32_e32 v101, v101
	v_fma_f32 v102, v102, s43, -v151
	v_exp_f32_e32 v102, v102
	s_waitcnt lgkmcnt(10)
	v_mfma_f32_32x32x16_bf16 v[32:47], v[252:255], v[204:207], v[32:47]
	v_fma_f32 v103, v103, s43, -v151
	v_exp_f32_e32 v103, v103
	v_add_f32_e32 v0, v96, v97
	v_add_f32_e32 v14, v98, v99
	v_add_f32_e32 v15, v100, v101
	v_add_f32_e32 v0, v0, v102
	v_add_f32_e32 v14, v14, v103
	s_waitcnt lgkmcnt(8)
	v_mfma_f32_32x32x16_bf16 v[16:31], v[216:219], v[204:207], v[16:31]
	v_cvt_pk_bf16_f32 v200, v96, v97
	v_cvt_pk_bf16_f32 v201, v98, v99
	v_cvt_pk_bf16_f32 v202, v100, v101
	v_cvt_pk_bf16_f32 v203, v102, v103
	s_waitcnt lgkmcnt(6)
	v_mfma_f32_32x32x16_bf16 v[64:79], v[2:5], v[208:211], v[64:79]
	ds_read_b64_tr_b16 v[156:157], v248 offset:20480
	ds_read_b64_tr_b16 v[158:159], v248 offset:22528
	ds_read_b64_tr_b16 v[160:161], v249 offset:20480
	ds_read_b64_tr_b16 v[162:163], v249 offset:22528
	ds_read_b64_tr_b16 v[252:253], v250 offset:20480
	ds_read_b64_tr_b16 v[254:255], v250 offset:22528
	ds_read_b64_tr_b16 v[216:217], v251 offset:20480
	ds_read_b64_tr_b16 v[218:219], v251 offset:22528
	v_fma_f32 v104, v104, s43, -v151
	v_exp_f32_e32 v104, v104
	v_fma_f32 v105, v105, s43, -v151
	v_exp_f32_e32 v105, v105
	v_fma_f32 v106, v106, s43, -v151
	v_exp_f32_e32 v106, v106
	v_fma_f32 v107, v107, s43, -v151
	s_waitcnt lgkmcnt(12)
	v_mfma_f32_32x32x16_bf16 v[48:63], v[6:9], v[208:211], v[48:63]
	v_exp_f32_e32 v107, v107
	v_fma_f32 v108, v108, s43, -v151
	v_exp_f32_e32 v108, v108
	v_fma_f32 v109, v109, s43, -v151
	v_exp_f32_e32 v109, v109
	v_fma_f32 v110, v110, s43, -v151
	v_exp_f32_e32 v110, v110
	s_waitcnt lgkmcnt(10)
	v_mfma_f32_32x32x16_bf16 v[32:47], v[10:13], v[208:211], v[32:47]
	v_fma_f32 v111, v111, s43, -v151
	v_exp_f32_e32 v111, v111
	v_add_f32_e32 v0, v0, v104
	v_add_f32_e32 v14, v14, v105
	v_add_f32_e32 v15, v15, v106
	v_add_f32_e32 v0, v0, v107
	v_add_f32_e32 v14, v14, v108
	s_waitcnt lgkmcnt(8)
	v_mfma_f32_32x32x16_bf16 v[16:31], v[244:247], v[208:211], v[16:31]
	v_add_f32_e32 v15, v15, v109
	v_add_f32_e32 v0, v0, v110
	v_add_f32_e32 v14, v14, v111
	v_cvt_pk_bf16_f32 v204, v104, v105
	v_cvt_pk_bf16_f32 v205, v106, v107
	v_cvt_pk_bf16_f32 v206, v108, v109
	v_cvt_pk_bf16_f32 v207, v110, v111
	s_waitcnt lgkmcnt(6)
	v_mfma_f32_32x32x16_bf16 v[64:79], v[156:159], v[220:223], v[64:79]
	v_fma_f32 v80, v80, s43, -v151
	v_exp_f32_e32 v80, v80
	v_fma_f32 v81, v81, s43, -v151
	v_exp_f32_e32 v81, v81
	v_fma_f32 v82, v82, s43, -v151
	v_exp_f32_e32 v82, v82
	v_fma_f32 v83, v83, s43, -v151
	s_waitcnt lgkmcnt(4)
	v_mfma_f32_32x32x16_bf16 v[48:63], v[160:163], v[220:223], v[48:63]
	v_exp_f32_e32 v83, v83
	v_fma_f32 v84, v84, s43, -v151
	v_exp_f32_e32 v84, v84
	v_fma_f32 v85, v85, s43, -v151
	v_exp_f32_e32 v85, v85
	v_fma_f32 v86, v86, s43, -v151
	v_exp_f32_e32 v86, v86
	s_waitcnt lgkmcnt(2)
	v_mfma_f32_32x32x16_bf16 v[32:47], v[252:255], v[220:223], v[32:47]
	v_fma_f32 v87, v87, s43, -v151
	v_exp_f32_e32 v87, v87
	v_add_f32_e32 v0, v0, v80
	v_add_f32_e32 v14, v14, v81
	v_add_f32_e32 v15, v15, v82
	v_add_f32_e32 v0, v0, v83
	v_add_f32_e32 v14, v14, v84
	s_waitcnt lgkmcnt(0)
	v_mfma_f32_32x32x16_bf16 v[16:31], v[216:219], v[220:223], v[16:31]
	v_add_f32_e32 v15, v15, v85
	v_add_f32_e32 v0, v0, v86
	v_add_f32_e32 v14, v14, v87
	v_cvt_pk_bf16_f32 v208, v80, v81
	v_cvt_pk_bf16_f32 v209, v82, v83
	v_cvt_pk_bf16_f32 v210, v84, v85
	v_cvt_pk_bf16_f32 v211, v86, v87
	v_fma_f32 v88, v88, s43, -v151
	v_exp_f32_e32 v88, v88
	v_fma_f32 v89, v89, s43, -v151
	v_exp_f32_e32 v89, v89
	v_fma_f32 v90, v90, s43, -v151
	v_exp_f32_e32 v90, v90
	v_fma_f32 v91, v91, s43, -v151
	v_exp_f32_e32 v91, v91
	v_fma_f32 v92, v92, s43, -v151
	v_exp_f32_e32 v92, v92
	v_fma_f32 v93, v93, s43, -v151
	v_exp_f32_e32 v93, v93
	v_fma_f32 v94, v94, s43, -v151
	v_exp_f32_e32 v94, v94
	v_fma_f32 v95, v95, s43, -v151
	v_exp_f32_e32 v95, v95
	v_add_f32_e32 v0, v0, v88
	v_add_f32_e32 v14, v14, v89
	v_add_f32_e32 v15, v15, v90
	v_add_f32_e32 v0, v0, v91
	v_add_f32_e32 v14, v14, v92
	v_add_f32_e32 v15, v15, v93
	v_add_f32_e32 v0, v0, v94
	v_add_f32_e32 v14, v14, v95
	v_cvt_pk_bf16_f32 v220, v88, v89
	v_cvt_pk_bf16_f32 v221, v90, v91
	v_cvt_pk_bf16_f32 v222, v92, v93
	v_cvt_pk_bf16_f32 v223, v94, v95
	v_add_f32_e32 v0, v0, v14
	v_add_f32_e32 v150, v150, v15
	v_add_f32_e32 v150, v150, v0
	s_mov_b32 s100, s38
	s_branch .LBB0_345
.Lq1_first:
	s_nop 10
	v_max3_f32 v0, v80, v81, v82
	v_max3_f32 v2, v83, v84, v85
	v_max3_f32 v3, v86, v87, v88
	v_max3_f32 v4, v89, v90, v91
	v_max3_f32 v0, v0, v92, v93
	v_max3_f32 v2, v2, v94, v95
	v_max3_f32 v3, v3, v96, v97
	v_max3_f32 v4, v4, v98, v99
	v_max3_f32 v0, v0, v100, v101
	v_max3_f32 v2, v2, v102, v103
	v_max3_f32 v3, v3, v104, v105
	v_max3_f32 v4, v4, v106, v107
	v_max3_f32 v0, v0, v108, v109
	v_max3_f32 v2, v2, v110, v111
	v_max3_f32 v0, v0, v3, v4
	v_max_f32_e32 v0, v0, v2
	v_mul_f32_e32 v0, 0x3e38aa3b, v0
	v_mov_b32_e32 v2, v0
	s_nop 1
	v_permlane32_swap_b32_e32 v0, v2
	v_max_f32_e32 v0, v0, v2
	v_add_f32_e32 v2, 0x41000000, v151
	v_cmp_gt_f32_e32 vcc, v0, v2
	s_cbranch_vccz .Lq1_fexp
	v_max_f32_e32 v0, v0, v0
	v_max_f32_e32 v2, v151, v151
	v_max_f32_e32 v2, v2, v0
	v_sub_f32_e32 v0, v151, v2
	v_exp_f32_e32 v0, v0
	v_mov_b32_e32 v151, v2
	v_pk_mul_f32 v[78:79], v[0:1], v[78:79] op_sel_hi:[0,1]
	v_pk_mul_f32 v[76:77], v[0:1], v[76:77] op_sel_hi:[0,1]
	v_pk_mul_f32 v[74:75], v[0:1], v[74:75] op_sel_hi:[0,1]
	v_pk_mul_f32 v[72:73], v[0:1], v[72:73] op_sel_hi:[0,1]
	v_pk_mul_f32 v[70:71], v[0:1], v[70:71] op_sel_hi:[0,1]
	v_pk_mul_f32 v[68:69], v[0:1], v[68:69] op_sel_hi:[0,1]
	v_pk_mul_f32 v[66:67], v[0:1], v[66:67] op_sel_hi:[0,1]
	v_pk_mul_f32 v[64:65], v[0:1], v[64:65] op_sel_hi:[0,1]
	v_pk_mul_f32 v[62:63], v[0:1], v[62:63] op_sel_hi:[0,1]
	v_pk_mul_f32 v[60:61], v[0:1], v[60:61] op_sel_hi:[0,1]
	v_pk_mul_f32 v[58:59], v[0:1], v[58:59] op_sel_hi:[0,1]
	v_pk_mul_f32 v[56:57], v[0:1], v[56:57] op_sel_hi:[0,1]
	v_pk_mul_f32 v[54:55], v[0:1], v[54:55] op_sel_hi:[0,1]
	v_pk_mul_f32 v[52:53], v[0:1], v[52:53] op_sel_hi:[0,1]
	v_pk_mul_f32 v[50:51], v[0:1], v[50:51] op_sel_hi:[0,1]
	v_pk_mul_f32 v[48:49], v[0:1], v[48:49] op_sel_hi:[0,1]
	v_pk_mul_f32 v[46:47], v[0:1], v[46:47] op_sel_hi:[0,1]
	v_pk_mul_f32 v[44:45], v[0:1], v[44:45] op_sel_hi:[0,1]
	v_pk_mul_f32 v[42:43], v[0:1], v[42:43] op_sel_hi:[0,1]
	v_pk_mul_f32 v[40:41], v[0:1], v[40:41] op_sel_hi:[0,1]
	v_pk_mul_f32 v[38:39], v[0:1], v[38:39] op_sel_hi:[0,1]
	v_pk_mul_f32 v[36:37], v[0:1], v[36:37] op_sel_hi:[0,1]
	v_pk_mul_f32 v[34:35], v[0:1], v[34:35] op_sel_hi:[0,1]
	v_pk_mul_f32 v[32:33], v[0:1], v[32:33] op_sel_hi:[0,1]
	v_pk_mul_f32 v[30:31], v[0:1], v[30:31] op_sel_hi:[0,1]
	v_pk_mul_f32 v[28:29], v[0:1], v[28:29] op_sel_hi:[0,1]
	v_pk_mul_f32 v[26:27], v[0:1], v[26:27] op_sel_hi:[0,1]
	v_pk_mul_f32 v[24:25], v[0:1], v[24:25] op_sel_hi:[0,1]
	v_pk_mul_f32 v[22:23], v[0:1], v[22:23] op_sel_hi:[0,1]
	v_pk_mul_f32 v[20:21], v[0:1], v[20:21] op_sel_hi:[0,1]
	v_pk_mul_f32 v[18:19], v[0:1], v[18:19] op_sel_hi:[0,1]
	v_pk_mul_f32 v[16:17], v[0:1], v[16:17] op_sel_hi:[0,1]
	v_mul_f32_e32 v150, v150, v0
.Lq1_fexp:
	v_fma_f32 v96, v96, s43, -v151
	v_exp_f32_e32 v96, v96
	v_fma_f32 v97, v97, s43, -v151
	v_exp_f32_e32 v97, v97
	v_fma_f32 v98, v98, s43, -v151
	v_exp_f32_e32 v98, v98
	v_fma_f32 v99, v99, s43, -v151
	v_exp_f32_e32 v99, v99
	v_fma_f32 v100, v100, s43, -v151
	v_exp_f32_e32 v100, v100
	v_fma_f32 v101, v101, s43, -v151
	v_exp_f32_e32 v101, v101
	v_fma_f32 v102, v102, s43, -v151
	v_exp_f32_e32 v102, v102
	v_fma_f32 v103, v103, s43, -v151
	v_exp_f32_e32 v103, v103
	v_add_f32_e32 v0, v96, v97
	v_add_f32_e32 v14, v98, v99
	v_add_f32_e32 v15, v100, v101
	v_add_f32_e32 v0, v0, v102
	v_add_f32_e32 v14, v14, v103
	v_cvt_pk_bf16_f32 v200, v96, v97
	v_cvt_pk_bf16_f32 v201, v98, v99
	v_cvt_pk_bf16_f32 v202, v100, v101
	v_cvt_pk_bf16_f32 v203, v102, v103
	v_fma_f32 v104, v104, s43, -v151
	v_exp_f32_e32 v104, v104
	v_fma_f32 v105, v105, s43, -v151
	v_exp_f32_e32 v105, v105
	v_fma_f32 v106, v106, s43, -v151
	v_exp_f32_e32 v106, v106
	v_fma_f32 v107, v107, s43, -v151
	v_exp_f32_e32 v107, v107
	v_fma_f32 v108, v108, s43, -v151
	v_exp_f32_e32 v108, v108
	v_fma_f32 v109, v109, s43, -v151
	v_exp_f32_e32 v109, v109
	v_fma_f32 v110, v110, s43, -v151
	v_exp_f32_e32 v110, v110
	v_fma_f32 v111, v111, s43, -v151
	v_exp_f32_e32 v111, v111
	v_add_f32_e32 v0, v0, v104
	v_add_f32_e32 v14, v14, v105
	v_add_f32_e32 v15, v15, v106
	v_add_f32_e32 v0, v0, v107
	v_add_f32_e32 v14, v14, v108
	v_add_f32_e32 v15, v15, v109
	v_add_f32_e32 v0, v0, v110
	v_add_f32_e32 v14, v14, v111
	v_cvt_pk_bf16_f32 v204, v104, v105
	v_cvt_pk_bf16_f32 v205, v106, v107
	v_cvt_pk_bf16_f32 v206, v108, v109
	v_cvt_pk_bf16_f32 v207, v110, v111
	v_fma_f32 v80, v80, s43, -v151
	v_exp_f32_e32 v80, v80
	v_fma_f32 v81, v81, s43, -v151
	v_exp_f32_e32 v81, v81
	v_fma_f32 v82, v82, s43, -v151
	v_exp_f32_e32 v82, v82
	v_fma_f32 v83, v83, s43, -v151
	v_exp_f32_e32 v83, v83
	v_fma_f32 v84, v84, s43, -v151
	v_exp_f32_e32 v84, v84
	v_fma_f32 v85, v85, s43, -v151
	v_exp_f32_e32 v85, v85
	v_fma_f32 v86, v86, s43, -v151
	v_exp_f32_e32 v86, v86
	v_fma_f32 v87, v87, s43, -v151
	v_exp_f32_e32 v87, v87
	v_add_f32_e32 v0, v0, v80
	v_add_f32_e32 v14, v14, v81
	v_add_f32_e32 v15, v15, v82
	v_add_f32_e32 v0, v0, v83
	v_add_f32_e32 v14, v14, v84
	v_add_f32_e32 v15, v15, v85
	v_add_f32_e32 v0, v0, v86
	v_add_f32_e32 v14, v14, v87
	v_cvt_pk_bf16_f32 v208, v80, v81
	v_cvt_pk_bf16_f32 v209, v82, v83
	v_cvt_pk_bf16_f32 v210, v84, v85
	v_cvt_pk_bf16_f32 v211, v86, v87
	v_fma_f32 v88, v88, s43, -v151
	v_exp_f32_e32 v88, v88
	v_fma_f32 v89, v89, s43, -v151
	v_exp_f32_e32 v89, v89
	v_fma_f32 v90, v90, s43, -v151
	v_exp_f32_e32 v90, v90
	v_fma_f32 v91, v91, s43, -v151
	v_exp_f32_e32 v91, v91
	v_fma_f32 v92, v92, s43, -v151
	v_exp_f32_e32 v92, v92
	v_fma_f32 v93, v93, s43, -v151
	v_exp_f32_e32 v93, v93
	v_fma_f32 v94, v94, s43, -v151
	v_exp_f32_e32 v94, v94
	v_fma_f32 v95, v95, s43, -v151
	v_exp_f32_e32 v95, v95
	v_add_f32_e32 v0, v0, v88
	v_add_f32_e32 v14, v14, v89
	v_add_f32_e32 v15, v15, v90
	v_add_f32_e32 v0, v0, v91
	v_add_f32_e32 v14, v14, v92
	v_add_f32_e32 v15, v15, v93
	v_add_f32_e32 v0, v0, v94
	v_add_f32_e32 v14, v14, v95
	v_cvt_pk_bf16_f32 v220, v88, v89
	v_cvt_pk_bf16_f32 v221, v90, v91
	v_cvt_pk_bf16_f32 v222, v92, v93
	v_cvt_pk_bf16_f32 v223, v94, v95
	v_add_f32_e32 v0, v0, v14
	v_add_f32_e32 v150, v150, v15
	v_add_f32_e32 v150, v150, v0
	s_mov_b32 s99, 1
	s_mov_b32 s100, s38
	s_branch .LBB0_345
.Lq1_exit:
	s_cmp_eq_u32 s99, 0
	s_cbranch_scc1 .LBB0_360
	v_add3_u32 v248, s100, v199, v187
	v_add3_u32 v249, s100, v199, v190
	v_add3_u32 v250, s100, v199, v191
	v_add3_u32 v251, s100, v199, v192
	ds_read_b64_tr_b16 v[2:3], v248 offset:8192
	ds_read_b64_tr_b16 v[4:5], v248 offset:10240
	ds_read_b64_tr_b16 v[6:7], v249 offset:8192
	ds_read_b64_tr_b16 v[8:9], v249 offset:10240
	ds_read_b64_tr_b16 v[10:11], v250 offset:8192
	ds_read_b64_tr_b16 v[12:13], v250 offset:10240
	ds_read_b64_tr_b16 v[244:245], v251 offset:8192
	ds_read_b64_tr_b16 v[246:247], v251 offset:10240
	s_waitcnt lgkmcnt(6)
	v_mfma_f32_32x32x16_bf16 v[64:79], v[2:5], v[200:203], v[64:79]
	ds_read_b64_tr_b16 v[156:157], v248 offset:12288
	ds_read_b64_tr_b16 v[158:159], v248 offset:14336
	ds_read_b64_tr_b16 v[160:161], v249 offset:12288
	ds_read_b64_tr_b16 v[162:163], v249 offset:14336
	ds_read_b64_tr_b16 v[252:253], v250 offset:12288
	ds_read_b64_tr_b16 v[254:255], v250 offset:14336
	ds_read_b64_tr_b16 v[216:217], v251 offset:12288
	ds_read_b64_tr_b16 v[218:219], v251 offset:14336
	s_waitcnt lgkmcnt(12)
	v_mfma_f32_32x32x16_bf16 v[48:63], v[6:9], v[200:203], v[48:63]
	s_waitcnt lgkmcnt(10)
	v_mfma_f32_32x32x16_bf16 v[32:47], v[10:13], v[200:203], v[32:47]
	s_waitcnt lgkmcnt(8)
	v_mfma_f32_32x32x16_bf16 v[16:31], v[244:247], v[200:203], v[16:31]
	s_waitcnt lgkmcnt(6)
	v_mfma_f32_32x32x16_bf16 v[64:79], v[156:159], v[204:207], v[64:79]
	ds_read_b64_tr_b16 v[2:3], v248 offset:16384
	ds_read_b64_tr_b16 v[4:5], v248 offset:18432
	ds_read_b64_tr_b16 v[6:7], v249 offset:16384
	ds_read_b64_tr_b16 v[8:9], v249 offset:18432
	ds_read_b64_tr_b16 v[10:11], v250 offset:16384
	ds_read_b64_tr_b16 v[12:13], v250 offset:18432
	ds_read_b64_tr_b16 v[244:245], v251 offset:16384
	ds_read_b64_tr_b16 v[246:247], v251 offset:18432
	s_waitcnt lgkmcnt(12)
	v_mfma_f32_32x32x16_bf16 v[48:63], v[160:163], v[204:207], v[48:63]
	s_waitcnt lgkmcnt(10)
	v_mfma_f32_32x32x16_bf16 v[32:47], v[252:255], v[204:207], v[32:47]
	s_waitcnt lgkmcnt(8)
	v_mfma_f32_32x32x16_bf16 v[16:31], v[216:219], v[204:207], v[16:31]
	s_waitcnt lgkmcnt(6)
	v_mfma_f32_32x32x16_bf16 v[64:79], v[2:5], v[208:211], v[64:79]
	ds_read_b64_tr_b16 v[156:157], v248 offset:20480
	ds_read_b64_tr_b16 v[158:159], v248 offset:22528
	ds_read_b64_tr_b16 v[160:161], v249 offset:20480
	ds_read_b64_tr_b16 v[162:163], v249 offset:22528
	ds_read_b64_tr_b16 v[252:253], v250 offset:20480
	ds_read_b64_tr_b16 v[254:255], v250 offset:22528
	ds_read_b64_tr_b16 v[216:217], v251 offset:20480
	ds_read_b64_tr_b16 v[218:219], v251 offset:22528
	s_waitcnt lgkmcnt(12)
	v_mfma_f32_32x32x16_bf16 v[48:63], v[6:9], v[208:211], v[48:63]
	s_waitcnt lgkmcnt(10)
	v_mfma_f32_32x32x16_bf16 v[32:47], v[10:13], v[208:211], v[32:47]
	s_waitcnt lgkmcnt(8)
	v_mfma_f32_32x32x16_bf16 v[16:31], v[244:247], v[208:211], v[16:31]
	s_waitcnt lgkmcnt(6)
	v_mfma_f32_32x32x16_bf16 v[64:79], v[156:159], v[220:223], v[64:79]
	s_waitcnt lgkmcnt(4)
	v_mfma_f32_32x32x16_bf16 v[48:63], v[160:163], v[220:223], v[48:63]
	s_waitcnt lgkmcnt(2)
	v_mfma_f32_32x32x16_bf16 v[32:47], v[252:255], v[220:223], v[32:47]
	s_waitcnt lgkmcnt(0)
	v_mfma_f32_32x32x16_bf16 v[16:31], v[216:219], v[220:223], v[16:31]
	s_mov_b32 s99, 0
	s_branch .LBB0_360

.LBB0_360:
	s_waitcnt lgkmcnt(0)
	s_barrier
	global_load_dwordx4 v[112:115], v[128:129], off offset:128
	global_load_dwordx4 v[116:119], v[128:129], off offset:160
	global_load_dwordx4 v[120:123], v[128:129], off offset:192
	global_load_dwordx4 v[124:127], v[128:129], off offset:224
	s_lshl_b32 s68, s92, 3
	v_mov_b32_e32 v81, 0
	v_or_b32_e32 v80, s68, v172
	v_lshrrev_b32_e32 v82, 1, v80
	v_xor_b32_e32 v82, v82, v215
	v_lshlrev_b32_e32 v82, 3, v82
	v_and_b32_e32 v86, 56, v82
	v_mul_lo_u32 v80, v80, s42
	v_or_b32_e32 v82, s68, v184
	v_or_b32_e32 v80, v86, v80
	s_lshl_b32 s69, s92, 10
	v_mul_lo_u32 v83, v82, s42
	v_lshl_add_u64 v[88:89], v[80:81], 1, s[30:31]
	v_or_b32_e32 v82, v83, v194
	v_add_u32_e32 v84, v83, v195
	v_lshl_add_u64 v[88:89], v[88:89], 0, s[18:19]
	s_mov_b32 m0, s69
	s_lshl_b32 s70, s92, 11
	v_mov_b32_e32 v83, 0
	global_load_lds_dwordx4 v[88:89], off
	v_lshl_add_u64 v[88:89], v[82:83], 1, s[30:31]
	s_add_i32 m0, s70, 0x2000
	v_lshl_add_u64 v[88:89], v[88:89], 0, s[12:13]
	v_mov_b32_e32 v85, 0
	global_load_lds_dwordx4 v[88:89], off
	v_lshl_add_u64 v[88:89], v[84:85], 1, s[26:27]
	s_add_i32 m0, s70, 0x2400
	s_nop 0
	global_load_lds_dwordx4 v[88:89], off
	s_add_u32 s72, s26, 0x60000
	v_lshl_add_u64 v[92:93], v[80:81], 1, s[28:29]
	s_addc_u32 s73, s27, 0
	v_lshlrev_b64 v[82:83], 1, v[82:83]
	v_lshl_add_u64 v[94:95], v[92:93], 0, s[20:21]
	s_add_i32 m0, s69, 0x6000
	v_lshl_add_u64 v[90:91], s[72:73], 0, v[82:83]
	global_load_lds_dwordx4 v[94:95], off
	s_add_i32 m0, s70, 0x8000
	v_lshlrev_b64 v[84:85], 1, v[84:85]
	global_load_lds_dwordx4 v[90:91], off
	s_add_i32 m0, s70, 0x8400
	v_lshl_add_u64 v[88:89], s[72:73], 0, v[84:85]
	s_add_u32 s74, s26, 0xc0000
	global_load_lds_dwordx4 v[88:89], off
	s_addc_u32 s75, s27, 0
	v_lshl_add_u64 v[88:89], v[92:93], 0, s[22:23]
	s_add_i32 m0, s69, 0xc000
	v_lshl_add_u64 v[82:83], s[74:75], 0, v[82:83]
	global_load_lds_dwordx4 v[88:89], off
	s_add_i32 m0, s70, 0xe000
	v_lshl_add_u64 v[84:85], s[74:75], 0, v[84:85]
	global_load_lds_dwordx4 v[82:83], off
	s_add_i32 m0, s70, 0xe400
	s_nop 0
	global_load_lds_dwordx4 v[84:85], off
	v_and_b32_e32 v2, 64, v193
	v_xor_b32_e32 v0, 32, v193
	v_add_u32_e32 v2, 64, v2
	v_cmp_lt_i32_e32 vcc, v0, v2
	s_xor_b64 s[24:25], s[36:37], -1
	v_mov_b32_e32 v3, s58
	v_cndmask_b32_e32 v0, v193, v0, vcc
	v_lshlrev_b32_e32 v198, 2, v0
	ds_bpermute_b32 v0, v198, v150
	v_or_b32_e32 v2, s57, v178
	v_lshlrev_b64 v[2:3], 11, v[2:3]
	v_lshl_add_u64 v[2:3], s[90:91], 0, v[2:3]
	v_lshl_add_u64 v[2:3], v[2:3], 0, s[4:5]
	s_waitcnt lgkmcnt(0)
	v_add_f32_e32 v0, v150, v0
	v_div_scale_f32 v4, s[36:37], v0, v0, 1.0
	v_rcp_f32_e32 v5, v4
	v_readfirstlane_b32 s4, v215
	s_lshr_b32 s37, s4, 6
	s_lshl_b32 s4, s37, 3
	v_fma_f32 v6, -v4, v5, 1.0
	v_fmac_f32_e32 v5, v6, v5
	v_div_scale_f32 v6, vcc, 1.0, v0, 1.0
	v_mul_f32_e32 v7, v6, v5
	v_fma_f32 v8, -v4, v7, v6
	v_fmac_f32_e32 v7, v8, v5
	v_fma_f32 v4, -v4, v7, v6
	v_div_fmas_f32 v4, v4, v5, v7
	v_div_fixup_f32 v0, v4, v0, 1.0
	v_pk_mul_f32 v[4:5], v[64:65], v[0:1] op_sel_hi:[1,0]
	v_pk_mul_f32 v[6:7], v[66:67], v[0:1] op_sel_hi:[1,0]
	v_pk_mul_f32 v[8:9], v[68:69], v[0:1] op_sel_hi:[1,0]
	v_pk_mul_f32 v[10:11], v[70:71], v[0:1] op_sel_hi:[1,0]
	v_pk_mul_f32 v[12:13], v[72:73], v[0:1] op_sel_hi:[1,0]
	v_pk_mul_f32 v[14:15], v[74:75], v[0:1] op_sel_hi:[1,0]
	v_pk_mul_f32 v[64:65], v[76:77], v[0:1] op_sel_hi:[1,0]
	v_pk_mul_f32 v[66:67], v[78:79], v[0:1] op_sel_hi:[1,0]
	v_pk_mul_f32 v[48:49], v[0:1], v[48:49] op_sel_hi:[0,1]
	v_pk_mul_f32 v[50:51], v[0:1], v[50:51] op_sel_hi:[0,1]
	v_pk_mul_f32 v[52:53], v[0:1], v[52:53] op_sel_hi:[0,1]
	v_pk_mul_f32 v[54:55], v[0:1], v[54:55] op_sel_hi:[0,1]
	v_pk_mul_f32 v[56:57], v[0:1], v[56:57] op_sel_hi:[0,1]
	v_pk_mul_f32 v[58:59], v[0:1], v[58:59] op_sel_hi:[0,1]
	v_pk_mul_f32 v[60:61], v[0:1], v[60:61] op_sel_hi:[0,1]
	v_pk_mul_f32 v[62:63], v[0:1], v[62:63] op_sel_hi:[0,1]
	v_pk_mul_f32 v[32:33], v[0:1], v[32:33] op_sel_hi:[0,1]
	v_pk_mul_f32 v[34:35], v[0:1], v[34:35] op_sel_hi:[0,1]
	v_pk_mul_f32 v[36:37], v[0:1], v[36:37] op_sel_hi:[0,1]
	v_pk_mul_f32 v[38:39], v[0:1], v[38:39] op_sel_hi:[0,1]
	v_pk_mul_f32 v[40:41], v[0:1], v[40:41] op_sel_hi:[0,1]
	v_pk_mul_f32 v[42:43], v[0:1], v[42:43] op_sel_hi:[0,1]
	v_pk_mul_f32 v[44:45], v[0:1], v[44:45] op_sel_hi:[0,1]
	v_pk_mul_f32 v[46:47], v[0:1], v[46:47] op_sel_hi:[0,1]
	v_pk_mul_f32 v[16:17], v[0:1], v[16:17] op_sel_hi:[0,1]
	v_pk_mul_f32 v[18:19], v[0:1], v[18:19] op_sel_hi:[0,1]
	v_pk_mul_f32 v[20:21], v[0:1], v[20:21] op_sel_hi:[0,1]
	v_pk_mul_f32 v[22:23], v[0:1], v[22:23] op_sel_hi:[0,1]
	v_pk_mul_f32 v[24:25], v[0:1], v[24:25] op_sel_hi:[0,1]
	v_pk_mul_f32 v[26:27], v[0:1], v[26:27] op_sel_hi:[0,1]
	v_pk_mul_f32 v[28:29], v[0:1], v[28:29] op_sel_hi:[0,1]
	v_pk_mul_f32 v[30:31], v[0:1], v[30:31] op_sel_hi:[0,1]
	v_lshlrev_b32_e32 v0, 1, v181
	v_lshl_add_u64 v[146:147], v[2:3], 0, v[0:1]
	v_cvt_pk_bf16_f32 v2, v4, v5
	v_cvt_pk_bf16_f32 v3, v6, v7
	global_store_dwordx2 v[146:147], v[2:3], off
	v_cvt_pk_bf16_f32 v2, v8, v9
	v_cvt_pk_bf16_f32 v3, v10, v11
	global_store_dwordx2 v[146:147], v[2:3], off offset:16
	v_cvt_pk_bf16_f32 v2, v12, v13
	v_cvt_pk_bf16_f32 v3, v14, v15
	global_store_dwordx2 v[146:147], v[2:3], off offset:32
	v_cvt_pk_bf16_f32 v2, v64, v65
	v_cvt_pk_bf16_f32 v3, v66, v67
	global_store_dwordx2 v[146:147], v[2:3], off offset:48
	v_cvt_pk_bf16_f32 v2, v48, v49
	v_cvt_pk_bf16_f32 v3, v50, v51
	global_store_dwordx2 v[146:147], v[2:3], off offset:64
	v_cvt_pk_bf16_f32 v2, v52, v53
	v_cvt_pk_bf16_f32 v3, v54, v55
	global_store_dwordx2 v[146:147], v[2:3], off offset:80
	v_cvt_pk_bf16_f32 v2, v56, v57
	v_cvt_pk_bf16_f32 v3, v58, v59
	global_store_dwordx2 v[146:147], v[2:3], off offset:96
	v_cvt_pk_bf16_f32 v2, v60, v61
	v_cvt_pk_bf16_f32 v3, v62, v63
	global_store_dwordx2 v[146:147], v[2:3], off offset:112
	v_cvt_pk_bf16_f32 v2, v32, v33
	v_cvt_pk_bf16_f32 v3, v34, v35
	global_store_dwordx2 v[146:147], v[2:3], off offset:128
	v_cvt_pk_bf16_f32 v2, v36, v37
	v_cvt_pk_bf16_f32 v3, v38, v39
	global_store_dwordx2 v[146:147], v[2:3], off offset:144
	v_cvt_pk_bf16_f32 v2, v40, v41
	v_cvt_pk_bf16_f32 v3, v42, v43
	global_store_dwordx2 v[146:147], v[2:3], off offset:160
	v_cvt_pk_bf16_f32 v2, v44, v45
	v_cvt_pk_bf16_f32 v3, v46, v47
	global_store_dwordx2 v[146:147], v[2:3], off offset:176
	v_cvt_pk_bf16_f32 v2, v16, v17
	v_cvt_pk_bf16_f32 v3, v18, v19
	global_store_dwordx2 v[146:147], v[2:3], off offset:192
	v_cvt_pk_bf16_f32 v2, v20, v21
	v_cvt_pk_bf16_f32 v3, v22, v23
	global_store_dwordx2 v[146:147], v[2:3], off offset:208
	v_cvt_pk_bf16_f32 v2, v24, v25
	v_cvt_pk_bf16_f32 v3, v26, v27
	global_store_dwordx2 v[146:147], v[2:3], off offset:224
	v_cvt_pk_bf16_f32 v2, v28, v29
	v_cvt_pk_bf16_f32 v3, v30, v31
	global_store_dwordx2 v[146:147], v[2:3], off offset:240
	v_or_b32_e32 v0, s4, v172
	v_lshrrev_b32_e32 v2, 1, v0
	v_xor_b32_e32 v2, v2, v215
	v_lshlrev_b32_e32 v2, 3, v2
	v_and_b32_e32 v6, 56, v2
	v_mul_lo_u32 v0, v0, s42
	v_or_b32_e32 v2, s4, v184
	v_or_b32_e32 v0, v6, v0
	s_lshl_b32 s4, s37, 10
	v_mul_lo_u32 v3, v2, s42
	v_lshl_add_u64 v[8:9], v[0:1], 1, s[30:31]
	s_add_i32 s39, s4, 0
	v_or_b32_e32 v2, v3, v194
	v_add_u32_e32 v4, v3, v195
	s_waitcnt vmcnt(0)
	s_waitcnt vmcnt(0)
	v_lshl_add_u64 v[8:9], v[8:9], 0, s[18:19]
	s_mov_b32 m0, s39
	s_lshl_b32 s36, s37, 11
	v_mov_b32_e32 v3, v1
	s_add_i32 s38, s36, 0
	v_lshl_add_u64 v[8:9], v[2:3], 1, s[30:31]
	s_add_i32 m0, s38, 0x2000
	v_lshl_add_u64 v[8:9], v[8:9], 0, s[12:13]
	v_mov_b32_e32 v5, v1
	v_lshl_add_u64 v[8:9], v[4:5], 1, s[26:27]
	s_add_i32 m0, s38, 0x2400
	s_andn2_b64 vcc, exec, s[34:35]
	s_cbranch_vccnz .LBB0_340
	s_add_u32 s30, s26, 0x60000
	v_lshl_add_u64 v[12:13], v[0:1], 1, s[28:29]
	s_addc_u32 s31, s27, 0
	v_lshlrev_b64 v[2:3], 1, v[2:3]
	v_lshl_add_u64 v[14:15], v[12:13], 0, s[20:21]
	s_add_i32 m0, s39, 0x6000
	v_lshl_add_u64 v[10:11], s[30:31], 0, v[2:3]
	s_add_i32 m0, s38, 0x8000
	v_lshlrev_b64 v[4:5], 1, v[4:5]
	s_add_i32 m0, s38, 0x8400
	v_lshl_add_u64 v[8:9], s[30:31], 0, v[4:5]
	s_add_u32 s26, s26, 0xc0000
	s_addc_u32 s27, s27, 0
	v_lshl_add_u64 v[8:9], v[12:13], 0, s[22:23]
	s_add_i32 m0, s39, 0xc000
	v_lshl_add_u64 v[2:3], s[26:27], 0, v[2:3]
	s_add_i32 m0, s38, 0xe000
	v_lshl_add_u64 v[4:5], s[26:27], 0, v[4:5]
	s_add_i32 m0, s38, 0xe400
	s_mulk_i32 s37, 0x6000
	s_and_b32 s26, s54, 3
	s_lshl_b32 s30, s55, 2
	v_add_u32_e32 v0, s37, v196
	s_lshl_b32 s26, s26, 8
	v_lshl_add_u64 v[128:129], v[0:1], 1, v[138:139]
	s_add_u32 s26, s56, s26
	v_add_u32_e32 v0, s37, v197
	s_addc_u32 s27, 0, 0
	v_lshl_add_u64 v[130:131], v[0:1], 1, v[138:139]
	v_add3_u32 v0, v188, s37, v6
	v_mov_b32_e32 v14, v1
	v_mov_b32_e32 v15, v1
	s_add_u32 s26, s50, s26
	v_lshl_add_u64 v[148:149], v[0:1], 1, v[142:143]
	v_mov_b32_e32 v0, v1
	v_mov_b32_e32 v2, v1
	v_mov_b32_e32 v3, v1
	v_mov_b32_e32 v4, v1
	v_mov_b32_e32 v5, v1
	v_mov_b32_e32 v6, v1
	v_mov_b32_e32 v7, v1
	v_mov_b32_e32 v8, v1
	v_mov_b32_e32 v9, v1
	v_mov_b32_e32 v10, v1
	v_mov_b32_e32 v11, v1
	v_mov_b32_e32 v12, v1
	v_mov_b32_e32 v13, v1
	v_mov_b64_e32 v[78:79], v[14:15]
	v_mov_b64_e32 v[62:63], v[14:15]
	v_mov_b64_e32 v[46:47], v[14:15]
	v_mov_b64_e32 v[30:31], v[14:15]
	s_addc_u32 s27, s51, s27
	s_sub_i32 s31, 31, s30
	s_mov_b32 s34, 0
	s_mov_b32 s98, 0
	s_mov_b32 s99, 0
	v_mov_b32_e32 v154, 0
	v_mov_b32_e32 v150, 0xf149f2ca
	v_mov_b64_e32 v[76:77], v[12:13]
	v_mov_b64_e32 v[74:75], v[10:11]
	v_mov_b64_e32 v[72:73], v[8:9]
	v_mov_b64_e32 v[70:71], v[6:7]
	v_mov_b64_e32 v[68:69], v[4:5]
	v_mov_b64_e32 v[66:67], v[2:3]
	v_mov_b64_e32 v[64:65], v[0:1]
	v_mov_b64_e32 v[60:61], v[12:13]
	v_mov_b64_e32 v[58:59], v[10:11]
	v_mov_b64_e32 v[56:57], v[8:9]
	v_mov_b64_e32 v[54:55], v[6:7]
	v_mov_b64_e32 v[52:53], v[4:5]
	v_mov_b64_e32 v[50:51], v[2:3]
	v_mov_b64_e32 v[48:49], v[0:1]
	v_mov_b64_e32 v[44:45], v[12:13]
	v_mov_b64_e32 v[42:43], v[10:11]
	v_mov_b64_e32 v[40:41], v[8:9]
	v_mov_b64_e32 v[38:39], v[6:7]
	v_mov_b64_e32 v[36:37], v[4:5]
	v_mov_b64_e32 v[34:35], v[2:3]
	v_mov_b64_e32 v[32:33], v[0:1]
	v_mov_b64_e32 v[28:29], v[12:13]
	v_mov_b64_e32 v[26:27], v[10:11]
	v_mov_b64_e32 v[24:25], v[8:9]
	v_mov_b64_e32 v[22:23], v[6:7]
	v_mov_b64_e32 v[20:21], v[4:5]
	v_mov_b64_e32 v[18:19], v[2:3]
	v_mov_b64_e32 v[16:17], v[0:1]
	s_branch .LBB0_364

.LBB0_363:
	s_add_i32 s34, s34, 1
	s_add_i32 s98, s98, 1
	s_cmp_eq_u32 s98, 5
	s_cselect_b32 s98, 0, s98
	s_add_i32 s28, s30, s34
	s_add_u32 s26, s26, 0x60000
	s_addc_u32 s27, s27, 0
	s_add_i32 s31, s31, -1
	s_cmp_lg_u32 s28, 32
	s_cbranch_scc0 .Lq2_exit

.LBB0_371:
	s_waitcnt lgkmcnt(0)
	s_barrier
	s_add_i32 s28, s34, 3
	s_cmp_ge_i32 s28, s53
	s_cbranch_scc1 .LBB0_373
	s_add_i32 s28, s98, 3
	s_add_i32 s101, s98, -2
	s_cmp_gt_u32 s28, 4
	s_cselect_b32 s28, s101, s28
	s_mulk_i32 s28, 0x6000
	s_add_i32 s28, s28, 0
	s_add_i32 m0, s28, s4
	s_add_i32 s28, s28, s36
	global_load_lds_dwordx4 v148, s[26:27]
	s_add_i32 m0, s28, 0x2000
	s_nop 0
	global_load_lds_dwordx4 v128, s[26:27]
	s_add_i32 m0, s28, 0x2400
	s_nop 0
	global_load_lds_dwordx4 v130, s[26:27]
.LBB0_373:
	s_branch .Lq2_body
.LBB0_376:
	s_branch .LBB0_367
.Lq2_body:
	s_cmp_gt_i32 s34, s52
	s_cbranch_scc0 .Lq2_work
	s_cmp_eq_u32 s99, 0
	s_cbranch_scc1 .LBB0_363
	v_add3_u32 v248, s100, v199, v187
	v_add3_u32 v249, s100, v199, v190
	v_add3_u32 v250, s100, v199, v191
	v_add3_u32 v251, s100, v199, v192
	ds_read_b64_tr_b16 v[2:3], v248 offset:8192
	ds_read_b64_tr_b16 v[4:5], v248 offset:10240
	ds_read_b64_tr_b16 v[6:7], v249 offset:8192
	ds_read_b64_tr_b16 v[8:9], v249 offset:10240
	ds_read_b64_tr_b16 v[10:11], v250 offset:8192
	ds_read_b64_tr_b16 v[12:13], v250 offset:10240
	ds_read_b64_tr_b16 v[244:245], v251 offset:8192
	ds_read_b64_tr_b16 v[246:247], v251 offset:10240
	s_waitcnt lgkmcnt(6)
	v_mfma_f32_32x32x16_bf16 v[16:31], v[2:5], v[200:203], v[16:31]
	ds_read_b64_tr_b16 v[156:157], v248 offset:12288
	ds_read_b64_tr_b16 v[158:159], v248 offset:14336
	ds_read_b64_tr_b16 v[160:161], v249 offset:12288
	ds_read_b64_tr_b16 v[162:163], v249 offset:14336
	ds_read_b64_tr_b16 v[252:253], v250 offset:12288
	ds_read_b64_tr_b16 v[254:255], v250 offset:14336
	ds_read_b64_tr_b16 v[216:217], v251 offset:12288
	ds_read_b64_tr_b16 v[218:219], v251 offset:14336
	s_waitcnt lgkmcnt(12)
	v_mfma_f32_32x32x16_bf16 v[32:47], v[6:9], v[200:203], v[32:47]
	s_waitcnt lgkmcnt(10)
	v_mfma_f32_32x32x16_bf16 v[48:63], v[10:13], v[200:203], v[48:63]
	s_waitcnt lgkmcnt(8)
	v_mfma_f32_32x32x16_bf16 v[64:79], v[244:247], v[200:203], v[64:79]
	s_waitcnt lgkmcnt(6)
	v_mfma_f32_32x32x16_bf16 v[16:31], v[156:159], v[204:207], v[16:31]
	ds_read_b64_tr_b16 v[2:3], v248 offset:16384
	ds_read_b64_tr_b16 v[4:5], v248 offset:18432
	ds_read_b64_tr_b16 v[6:7], v249 offset:16384
	ds_read_b64_tr_b16 v[8:9], v249 offset:18432
	ds_read_b64_tr_b16 v[10:11], v250 offset:16384
	ds_read_b64_tr_b16 v[12:13], v250 offset:18432
	ds_read_b64_tr_b16 v[244:245], v251 offset:16384
	ds_read_b64_tr_b16 v[246:247], v251 offset:18432
	s_waitcnt lgkmcnt(12)
	v_mfma_f32_32x32x16_bf16 v[32:47], v[160:163], v[204:207], v[32:47]
	s_waitcnt lgkmcnt(10)
	v_mfma_f32_32x32x16_bf16 v[48:63], v[252:255], v[204:207], v[48:63]
	s_waitcnt lgkmcnt(8)
	v_mfma_f32_32x32x16_bf16 v[64:79], v[216:219], v[204:207], v[64:79]
	s_waitcnt lgkmcnt(6)
	v_mfma_f32_32x32x16_bf16 v[16:31], v[2:5], v[208:211], v[16:31]
	ds_read_b64_tr_b16 v[156:157], v248 offset:20480
	ds_read_b64_tr_b16 v[158:159], v248 offset:22528
	ds_read_b64_tr_b16 v[160:161], v249 offset:20480
	ds_read_b64_tr_b16 v[162:163], v249 offset:22528
	ds_read_b64_tr_b16 v[252:253], v250 offset:20480
	ds_read_b64_tr_b16 v[254:255], v250 offset:22528
	ds_read_b64_tr_b16 v[216:217], v251 offset:20480
	ds_read_b64_tr_b16 v[218:219], v251 offset:22528
	s_waitcnt lgkmcnt(12)
	v_mfma_f32_32x32x16_bf16 v[32:47], v[6:9], v[208:211], v[32:47]
	s_waitcnt lgkmcnt(10)
	v_mfma_f32_32x32x16_bf16 v[48:63], v[10:13], v[208:211], v[48:63]
	s_waitcnt lgkmcnt(8)
	v_mfma_f32_32x32x16_bf16 v[64:79], v[244:247], v[208:211], v[64:79]
	s_waitcnt lgkmcnt(6)
	v_mfma_f32_32x32x16_bf16 v[16:31], v[156:159], v[220:223], v[16:31]
	s_waitcnt lgkmcnt(4)
	v_mfma_f32_32x32x16_bf16 v[32:47], v[160:163], v[220:223], v[32:47]
	s_waitcnt lgkmcnt(2)
	v_mfma_f32_32x32x16_bf16 v[48:63], v[252:255], v[220:223], v[48:63]
	s_waitcnt lgkmcnt(0)
	v_mfma_f32_32x32x16_bf16 v[64:79], v[216:219], v[220:223], v[64:79]
	s_mov_b32 s99, 0
	s_branch .LBB0_363
.Lq2_work:
	s_mov_b32 s28, s98
	s_mulk_i32 s28, 0x6000
	s_add_i32 s28, s28, 0
	v_add3_u32 v14, s28, v174, v173
	v_add3_u32 v15, s28, v174, v177
	ds_read_b128 v[2:5], v14
	ds_read_b128 v[6:9], v14 offset:4096
	ds_read_b128 v[10:13], v15
	ds_read_b128 v[252:255], v15 offset:4096
	v_add3_u32 v14, s28, v174, v179
	v_add3_u32 v15, s28, v174, v180
	ds_read_b128 v[156:159], v14
	ds_read_b128 v[160:163], v14 offset:4096
	ds_read_b128 v[244:247], v15
	ds_read_b128 v[248:251], v15 offset:4096
	s_waitcnt lgkmcnt(6)
	v_mfma_f32_32x32x16_bf16 v[96:111], v[2:5], v[112:115], 0
	v_mfma_f32_32x32x16_bf16 v[80:95], v[6:9], v[112:115], 0
	s_waitcnt lgkmcnt(4)
	v_mfma_f32_32x32x16_bf16 v[96:111], v[10:13], v[116:119], v[96:111]
	v_mfma_f32_32x32x16_bf16 v[80:95], v[252:255], v[116:119], v[80:95]
	s_waitcnt lgkmcnt(2)
	v_mfma_f32_32x32x16_bf16 v[96:111], v[156:159], v[120:123], v[96:111]
	v_mfma_f32_32x32x16_bf16 v[80:95], v[160:163], v[120:123], v[80:95]
	s_waitcnt lgkmcnt(0)
	v_mfma_f32_32x32x16_bf16 v[80:95], v[248:251], v[124:127], v[80:95]
	v_mfma_f32_32x32x16_bf16 v[96:111], v[244:247], v[124:127], v[96:111]
	s_cmp_eq_u32 s99, 0
	s_cbranch_scc1 .Lq2_first
	v_add3_u32 v248, s100, v199, v187
	v_add3_u32 v249, s100, v199, v190
	v_add3_u32 v250, s100, v199, v191
	v_add3_u32 v251, s100, v199, v192
	ds_read_b64_tr_b16 v[2:3], v248 offset:8192
	ds_read_b64_tr_b16 v[4:5], v248 offset:10240
	ds_read_b64_tr_b16 v[6:7], v249 offset:8192
	ds_read_b64_tr_b16 v[8:9], v249 offset:10240
	ds_read_b64_tr_b16 v[10:11], v250 offset:8192
	ds_read_b64_tr_b16 v[12:13], v250 offset:10240
	ds_read_b64_tr_b16 v[244:245], v251 offset:8192
	ds_read_b64_tr_b16 v[246:247], v251 offset:10240
	s_waitcnt lgkmcnt(6)
	v_mfma_f32_32x32x16_bf16 v[16:31], v[2:5], v[200:203], v[16:31]
	ds_read_b64_tr_b16 v[156:157], v248 offset:12288
	ds_read_b64_tr_b16 v[158:159], v248 offset:14336
	ds_read_b64_tr_b16 v[160:161], v249 offset:12288
	ds_read_b64_tr_b16 v[162:163], v249 offset:14336
	ds_read_b64_tr_b16 v[252:253], v250 offset:12288
	ds_read_b64_tr_b16 v[254:255], v250 offset:14336
	ds_read_b64_tr_b16 v[216:217], v251 offset:12288
	ds_read_b64_tr_b16 v[218:219], v251 offset:14336
	s_waitcnt lgkmcnt(12)
	v_mfma_f32_32x32x16_bf16 v[32:47], v[6:9], v[200:203], v[32:47]
	s_waitcnt lgkmcnt(10)
	v_mfma_f32_32x32x16_bf16 v[48:63], v[10:13], v[200:203], v[48:63]
	s_waitcnt lgkmcnt(8)
	v_mfma_f32_32x32x16_bf16 v[64:79], v[244:247], v[200:203], v[64:79]
	v_max3_f32 v0, v80, v81, v82
	v_max3_f32 v2, v83, v84, v85
	v_max3_f32 v3, v86, v87, v88
	v_max3_f32 v4, v89, v90, v91
	v_max3_f32 v0, v0, v92, v93
	v_max3_f32 v2, v2, v94, v95
	v_max3_f32 v3, v3, v96, v97
	v_max3_f32 v4, v4, v98, v99
	v_max3_f32 v0, v0, v100, v101
	v_max3_f32 v2, v2, v102, v103
	v_max3_f32 v3, v3, v104, v105
	v_max3_f32 v4, v4, v106, v107
	v_max3_f32 v0, v0, v108, v109
	v_max3_f32 v2, v2, v110, v111
	v_max3_f32 v0, v0, v3, v4
	v_max_f32_e32 v0, v0, v2
	v_mul_f32_e32 v0, 0x3e38aa3b, v0
	v_mov_b32_e32 v2, v0
	s_nop 1
	v_permlane32_swap_b32_e32 v0, v2
	v_max_f32_e32 v0, v0, v2
	v_add_f32_e32 v2, 0x41000000, v150
	v_cmp_gt_f32_e32 vcc, v0, v2
	s_cbranch_vccz .Lq2_fast
	s_waitcnt lgkmcnt(6)
	v_mfma_f32_32x32x16_bf16 v[16:31], v[156:159], v[204:207], v[16:31]
	ds_read_b64_tr_b16 v[2:3], v248 offset:16384
	ds_read_b64_tr_b16 v[4:5], v248 offset:18432
	ds_read_b64_tr_b16 v[6:7], v249 offset:16384
	ds_read_b64_tr_b16 v[8:9], v249 offset:18432
	ds_read_b64_tr_b16 v[10:11], v250 offset:16384
	ds_read_b64_tr_b16 v[12:13], v250 offset:18432
	ds_read_b64_tr_b16 v[244:245], v251 offset:16384
	ds_read_b64_tr_b16 v[246:247], v251 offset:18432
	s_waitcnt lgkmcnt(12)
	v_mfma_f32_32x32x16_bf16 v[32:47], v[160:163], v[204:207], v[32:47]
	s_waitcnt lgkmcnt(10)
	v_mfma_f32_32x32x16_bf16 v[48:63], v[252:255], v[204:207], v[48:63]
	s_waitcnt lgkmcnt(8)
	v_mfma_f32_32x32x16_bf16 v[64:79], v[216:219], v[204:207], v[64:79]
	s_waitcnt lgkmcnt(6)
	v_mfma_f32_32x32x16_bf16 v[16:31], v[2:5], v[208:211], v[16:31]
	ds_read_b64_tr_b16 v[156:157], v248 offset:20480
	ds_read_b64_tr_b16 v[158:159], v248 offset:22528
	ds_read_b64_tr_b16 v[160:161], v249 offset:20480
	ds_read_b64_tr_b16 v[162:163], v249 offset:22528
	ds_read_b64_tr_b16 v[252:253], v250 offset:20480
	ds_read_b64_tr_b16 v[254:255], v250 offset:22528
	ds_read_b64_tr_b16 v[216:217], v251 offset:20480
	ds_read_b64_tr_b16 v[218:219], v251 offset:22528
	s_waitcnt lgkmcnt(12)
	v_mfma_f32_32x32x16_bf16 v[32:47], v[6:9], v[208:211], v[32:47]
	s_waitcnt lgkmcnt(10)
	v_mfma_f32_32x32x16_bf16 v[48:63], v[10:13], v[208:211], v[48:63]
	s_waitcnt lgkmcnt(8)
	v_mfma_f32_32x32x16_bf16 v[64:79], v[244:247], v[208:211], v[64:79]
	s_waitcnt lgkmcnt(6)
	v_mfma_f32_32x32x16_bf16 v[16:31], v[156:159], v[220:223], v[16:31]
	s_waitcnt lgkmcnt(4)
	v_mfma_f32_32x32x16_bf16 v[32:47], v[160:163], v[220:223], v[32:47]
	s_waitcnt lgkmcnt(2)
	v_mfma_f32_32x32x16_bf16 v[48:63], v[252:255], v[220:223], v[48:63]
	s_waitcnt lgkmcnt(0)
	v_mfma_f32_32x32x16_bf16 v[64:79], v[216:219], v[220:223], v[64:79]
	s_nop 7
	s_nop 7
	v_max_f32_e32 v0, v0, v0
	v_max_f32_e32 v2, v150, v150
	v_max_f32_e32 v2, v2, v0
	v_sub_f32_e32 v0, v150, v2
	v_exp_f32_e32 v0, v0
	v_mov_b32_e32 v150, v2
	v_pk_mul_f32 v[30:31], v[30:31], v[0:1] op_sel_hi:[1,0]
	v_pk_mul_f32 v[28:29], v[28:29], v[0:1] op_sel_hi:[1,0]
	v_pk_mul_f32 v[26:27], v[26:27], v[0:1] op_sel_hi:[1,0]
	v_pk_mul_f32 v[24:25], v[24:25], v[0:1] op_sel_hi:[1,0]
	v_pk_mul_f32 v[22:23], v[22:23], v[0:1] op_sel_hi:[1,0]
	v_pk_mul_f32 v[20:21], v[20:21], v[0:1] op_sel_hi:[1,0]
	v_pk_mul_f32 v[18:19], v[18:19], v[0:1] op_sel_hi:[1,0]
	v_pk_mul_f32 v[16:17], v[16:17], v[0:1] op_sel_hi:[1,0]
	v_pk_mul_f32 v[46:47], v[46:47], v[0:1] op_sel_hi:[1,0]
	v_pk_mul_f32 v[44:45], v[44:45], v[0:1] op_sel_hi:[1,0]
	v_pk_mul_f32 v[42:43], v[42:43], v[0:1] op_sel_hi:[1,0]
	v_pk_mul_f32 v[40:41], v[40:41], v[0:1] op_sel_hi:[1,0]
	v_pk_mul_f32 v[38:39], v[38:39], v[0:1] op_sel_hi:[1,0]
	v_pk_mul_f32 v[36:37], v[36:37], v[0:1] op_sel_hi:[1,0]
	v_pk_mul_f32 v[34:35], v[34:35], v[0:1] op_sel_hi:[1,0]
	v_pk_mul_f32 v[32:33], v[32:33], v[0:1] op_sel_hi:[1,0]
	v_pk_mul_f32 v[62:63], v[62:63], v[0:1] op_sel_hi:[1,0]
	v_pk_mul_f32 v[60:61], v[60:61], v[0:1] op_sel_hi:[1,0]
	v_pk_mul_f32 v[58:59], v[58:59], v[0:1] op_sel_hi:[1,0]
	v_pk_mul_f32 v[56:57], v[56:57], v[0:1] op_sel_hi:[1,0]
	v_pk_mul_f32 v[54:55], v[54:55], v[0:1] op_sel_hi:[1,0]
	v_pk_mul_f32 v[52:53], v[52:53], v[0:1] op_sel_hi:[1,0]
	v_pk_mul_f32 v[50:51], v[50:51], v[0:1] op_sel_hi:[1,0]
	v_pk_mul_f32 v[48:49], v[48:49], v[0:1] op_sel_hi:[1,0]
	v_pk_mul_f32 v[78:79], v[78:79], v[0:1] op_sel_hi:[1,0]
	v_pk_mul_f32 v[76:77], v[76:77], v[0:1] op_sel_hi:[1,0]
	v_pk_mul_f32 v[74:75], v[74:75], v[0:1] op_sel_hi:[1,0]
	v_pk_mul_f32 v[72:73], v[72:73], v[0:1] op_sel_hi:[1,0]
	v_pk_mul_f32 v[70:71], v[70:71], v[0:1] op_sel_hi:[1,0]
	v_pk_mul_f32 v[68:69], v[68:69], v[0:1] op_sel_hi:[1,0]
	v_pk_mul_f32 v[66:67], v[66:67], v[0:1] op_sel_hi:[1,0]
	v_pk_mul_f32 v[64:65], v[64:65], v[0:1] op_sel_hi:[1,0]
	v_mul_f32_e32 v154, v154, v0
	v_fma_f32 v96, v96, s43, -v150
	v_exp_f32_e32 v96, v96
	v_fma_f32 v97, v97, s43, -v150
	v_exp_f32_e32 v97, v97
	v_fma_f32 v98, v98, s43, -v150
	v_exp_f32_e32 v98, v98
	v_fma_f32 v99, v99, s43, -v150
	v_exp_f32_e32 v99, v99
	v_fma_f32 v100, v100, s43, -v150
	v_exp_f32_e32 v100, v100
	v_fma_f32 v101, v101, s43, -v150
	v_exp_f32_e32 v101, v101
	v_fma_f32 v102, v102, s43, -v150
	v_exp_f32_e32 v102, v102
	v_fma_f32 v103, v103, s43, -v150
	v_exp_f32_e32 v103, v103
	v_add_f32_e32 v0, v96, v97
	v_add_f32_e32 v14, v98, v99
	v_add_f32_e32 v15, v100, v101
	v_add_f32_e32 v0, v0, v102
	v_add_f32_e32 v14, v14, v103
	v_cvt_pk_bf16_f32 v200, v96, v97
	v_cvt_pk_bf16_f32 v201, v98, v99
	v_cvt_pk_bf16_f32 v202, v100, v101
	v_cvt_pk_bf16_f32 v203, v102, v103
	v_fma_f32 v104, v104, s43, -v150
	v_exp_f32_e32 v104, v104
	v_fma_f32 v105, v105, s43, -v150
	v_exp_f32_e32 v105, v105
	v_fma_f32 v106, v106, s43, -v150
	v_exp_f32_e32 v106, v106
	v_fma_f32 v107, v107, s43, -v150
	v_exp_f32_e32 v107, v107
	v_fma_f32 v108, v108, s43, -v150
	v_exp_f32_e32 v108, v108
	v_fma_f32 v109, v109, s43, -v150
	v_exp_f32_e32 v109, v109
	v_fma_f32 v110, v110, s43, -v150
	v_exp_f32_e32 v110, v110
	v_fma_f32 v111, v111, s43, -v150
	v_exp_f32_e32 v111, v111
	v_add_f32_e32 v0, v0, v104
	v_add_f32_e32 v14, v14, v105
	v_add_f32_e32 v15, v15, v106
	v_add_f32_e32 v0, v0, v107
	v_add_f32_e32 v14, v14, v108
	v_add_f32_e32 v15, v15, v109
	v_add_f32_e32 v0, v0, v110
	v_add_f32_e32 v14, v14, v111
	v_cvt_pk_bf16_f32 v204, v104, v105
	v_cvt_pk_bf16_f32 v205, v106, v107
	v_cvt_pk_bf16_f32 v206, v108, v109
	v_cvt_pk_bf16_f32 v207, v110, v111
	v_fma_f32 v80, v80, s43, -v150
	v_exp_f32_e32 v80, v80
	v_fma_f32 v81, v81, s43, -v150
	v_exp_f32_e32 v81, v81
	v_fma_f32 v82, v82, s43, -v150
	v_exp_f32_e32 v82, v82
	v_fma_f32 v83, v83, s43, -v150
	v_exp_f32_e32 v83, v83
	v_fma_f32 v84, v84, s43, -v150
	v_exp_f32_e32 v84, v84
	v_fma_f32 v85, v85, s43, -v150
	v_exp_f32_e32 v85, v85
	v_fma_f32 v86, v86, s43, -v150
	v_exp_f32_e32 v86, v86
	v_fma_f32 v87, v87, s43, -v150
	v_exp_f32_e32 v87, v87
	v_add_f32_e32 v0, v0, v80
	v_add_f32_e32 v14, v14, v81
	v_add_f32_e32 v15, v15, v82
	v_add_f32_e32 v0, v0, v83
	v_add_f32_e32 v14, v14, v84
	v_add_f32_e32 v15, v15, v85
	v_add_f32_e32 v0, v0, v86
	v_add_f32_e32 v14, v14, v87
	v_cvt_pk_bf16_f32 v208, v80, v81
	v_cvt_pk_bf16_f32 v209, v82, v83
	v_cvt_pk_bf16_f32 v210, v84, v85
	v_cvt_pk_bf16_f32 v211, v86, v87
	v_fma_f32 v88, v88, s43, -v150
	v_exp_f32_e32 v88, v88
	v_fma_f32 v89, v89, s43, -v150
	v_exp_f32_e32 v89, v89
	v_fma_f32 v90, v90, s43, -v150
	v_exp_f32_e32 v90, v90
	v_fma_f32 v91, v91, s43, -v150
	v_exp_f32_e32 v91, v91
	v_fma_f32 v92, v92, s43, -v150
	v_exp_f32_e32 v92, v92
	v_fma_f32 v93, v93, s43, -v150
	v_exp_f32_e32 v93, v93
	v_fma_f32 v94, v94, s43, -v150
	v_exp_f32_e32 v94, v94
	v_fma_f32 v95, v95, s43, -v150
	v_exp_f32_e32 v95, v95
	v_add_f32_e32 v0, v0, v88
	v_add_f32_e32 v14, v14, v89
	v_add_f32_e32 v15, v15, v90
	v_add_f32_e32 v0, v0, v91
	v_add_f32_e32 v14, v14, v92
	v_add_f32_e32 v15, v15, v93
	v_add_f32_e32 v0, v0, v94
	v_add_f32_e32 v14, v14, v95
	v_cvt_pk_bf16_f32 v220, v88, v89
	v_cvt_pk_bf16_f32 v221, v90, v91
	v_cvt_pk_bf16_f32 v222, v92, v93
	v_cvt_pk_bf16_f32 v223, v94, v95
	v_add_f32_e32 v0, v0, v14
	v_add_f32_e32 v154, v154, v15
	v_add_f32_e32 v154, v154, v0
	s_mov_b32 s100, s28
	s_branch .LBB0_363
.Lq2_fast:
	s_waitcnt lgkmcnt(6)
	v_mfma_f32_32x32x16_bf16 v[16:31], v[156:159], v[204:207], v[16:31]
	ds_read_b64_tr_b16 v[2:3], v248 offset:16384
	ds_read_b64_tr_b16 v[4:5], v248 offset:18432
	ds_read_b64_tr_b16 v[6:7], v249 offset:16384
	ds_read_b64_tr_b16 v[8:9], v249 offset:18432
	ds_read_b64_tr_b16 v[10:11], v250 offset:16384
	ds_read_b64_tr_b16 v[12:13], v250 offset:18432
	ds_read_b64_tr_b16 v[244:245], v251 offset:16384
	ds_read_b64_tr_b16 v[246:247], v251 offset:18432
	v_fma_f32 v96, v96, s43, -v150
	v_exp_f32_e32 v96, v96
	v_fma_f32 v97, v97, s43, -v150
	v_exp_f32_e32 v97, v97
	v_fma_f32 v98, v98, s43, -v150
	v_exp_f32_e32 v98, v98
	v_fma_f32 v99, v99, s43, -v150
	s_waitcnt lgkmcnt(12)
	v_mfma_f32_32x32x16_bf16 v[32:47], v[160:163], v[204:207], v[32:47]
	v_exp_f32_e32 v99, v99
	v_fma_f32 v100, v100, s43, -v150
	v_exp_f32_e32 v100, v100
	v_fma_f32 v101, v101, s43, -v150
	v_exp_f32_e32 v101, v101
	v_fma_f32 v102, v102, s43, -v150
	v_exp_f32_e32 v102, v102
	s_waitcnt lgkmcnt(10)
	v_mfma_f32_32x32x16_bf16 v[48:63], v[252:255], v[204:207], v[48:63]
	v_fma_f32 v103, v103, s43, -v150
	v_exp_f32_e32 v103, v103
	v_add_f32_e32 v0, v96, v97
	v_add_f32_e32 v14, v98, v99
	v_add_f32_e32 v15, v100, v101
	v_add_f32_e32 v0, v0, v102
	v_add_f32_e32 v14, v14, v103
	s_waitcnt lgkmcnt(8)
	v_mfma_f32_32x32x16_bf16 v[64:79], v[216:219], v[204:207], v[64:79]
	v_cvt_pk_bf16_f32 v200, v96, v97
	v_cvt_pk_bf16_f32 v201, v98, v99
	v_cvt_pk_bf16_f32 v202, v100, v101
	v_cvt_pk_bf16_f32 v203, v102, v103
	s_waitcnt lgkmcnt(6)
	v_mfma_f32_32x32x16_bf16 v[16:31], v[2:5], v[208:211], v[16:31]
	ds_read_b64_tr_b16 v[156:157], v248 offset:20480
	ds_read_b64_tr_b16 v[158:159], v248 offset:22528
	ds_read_b64_tr_b16 v[160:161], v249 offset:20480
	ds_read_b64_tr_b16 v[162:163], v249 offset:22528
	ds_read_b64_tr_b16 v[252:253], v250 offset:20480
	ds_read_b64_tr_b16 v[254:255], v250 offset:22528
	ds_read_b64_tr_b16 v[216:217], v251 offset:20480
	ds_read_b64_tr_b16 v[218:219], v251 offset:22528
	v_fma_f32 v104, v104, s43, -v150
	v_exp_f32_e32 v104, v104
	v_fma_f32 v105, v105, s43, -v150
	v_exp_f32_e32 v105, v105
	v_fma_f32 v106, v106, s43, -v150
	v_exp_f32_e32 v106, v106
	v_fma_f32 v107, v107, s43, -v150
	s_waitcnt lgkmcnt(12)
	v_mfma_f32_32x32x16_bf16 v[32:47], v[6:9], v[208:211], v[32:47]
	v_exp_f32_e32 v107, v107
	v_fma_f32 v108, v108, s43, -v150
	v_exp_f32_e32 v108, v108
	v_fma_f32 v109, v109, s43, -v150
	v_exp_f32_e32 v109, v109
	v_fma_f32 v110, v110, s43, -v150
	v_exp_f32_e32 v110, v110
	s_waitcnt lgkmcnt(10)
	v_mfma_f32_32x32x16_bf16 v[48:63], v[10:13], v[208:211], v[48:63]
	v_fma_f32 v111, v111, s43, -v150
	v_exp_f32_e32 v111, v111
	v_add_f32_e32 v0, v0, v104
	v_add_f32_e32 v14, v14, v105
	v_add_f32_e32 v15, v15, v106
	v_add_f32_e32 v0, v0, v107
	v_add_f32_e32 v14, v14, v108
	s_waitcnt lgkmcnt(8)
	v_mfma_f32_32x32x16_bf16 v[64:79], v[244:247], v[208:211], v[64:79]
	v_add_f32_e32 v15, v15, v109
	v_add_f32_e32 v0, v0, v110
	v_add_f32_e32 v14, v14, v111
	v_cvt_pk_bf16_f32 v204, v104, v105
	v_cvt_pk_bf16_f32 v205, v106, v107
	v_cvt_pk_bf16_f32 v206, v108, v109
	v_cvt_pk_bf16_f32 v207, v110, v111
	s_waitcnt lgkmcnt(6)
	v_mfma_f32_32x32x16_bf16 v[16:31], v[156:159], v[220:223], v[16:31]
	v_fma_f32 v80, v80, s43, -v150
	v_exp_f32_e32 v80, v80
	v_fma_f32 v81, v81, s43, -v150
	v_exp_f32_e32 v81, v81
	v_fma_f32 v82, v82, s43, -v150
	v_exp_f32_e32 v82, v82
	v_fma_f32 v83, v83, s43, -v150
	s_waitcnt lgkmcnt(4)
	v_mfma_f32_32x32x16_bf16 v[32:47], v[160:163], v[220:223], v[32:47]
	v_exp_f32_e32 v83, v83
	v_fma_f32 v84, v84, s43, -v150
	v_exp_f32_e32 v84, v84
	v_fma_f32 v85, v85, s43, -v150
	v_exp_f32_e32 v85, v85
	v_fma_f32 v86, v86, s43, -v150
	v_exp_f32_e32 v86, v86
	s_waitcnt lgkmcnt(2)
	v_mfma_f32_32x32x16_bf16 v[48:63], v[252:255], v[220:223], v[48:63]
	v_fma_f32 v87, v87, s43, -v150
	v_exp_f32_e32 v87, v87
	v_add_f32_e32 v0, v0, v80
	v_add_f32_e32 v14, v14, v81
	v_add_f32_e32 v15, v15, v82
	v_add_f32_e32 v0, v0, v83
	v_add_f32_e32 v14, v14, v84
	s_waitcnt lgkmcnt(0)
	v_mfma_f32_32x32x16_bf16 v[64:79], v[216:219], v[220:223], v[64:79]
	v_add_f32_e32 v15, v15, v85
	v_add_f32_e32 v0, v0, v86
	v_add_f32_e32 v14, v14, v87
	v_cvt_pk_bf16_f32 v208, v80, v81
	v_cvt_pk_bf16_f32 v209, v82, v83
	v_cvt_pk_bf16_f32 v210, v84, v85
	v_cvt_pk_bf16_f32 v211, v86, v87
	v_fma_f32 v88, v88, s43, -v150
	v_exp_f32_e32 v88, v88
	v_fma_f32 v89, v89, s43, -v150
	v_exp_f32_e32 v89, v89
	v_fma_f32 v90, v90, s43, -v150
	v_exp_f32_e32 v90, v90
	v_fma_f32 v91, v91, s43, -v150
	v_exp_f32_e32 v91, v91
	v_fma_f32 v92, v92, s43, -v150
	v_exp_f32_e32 v92, v92
	v_fma_f32 v93, v93, s43, -v150
	v_exp_f32_e32 v93, v93
	v_fma_f32 v94, v94, s43, -v150
	v_exp_f32_e32 v94, v94
	v_fma_f32 v95, v95, s43, -v150
	v_exp_f32_e32 v95, v95
	v_add_f32_e32 v0, v0, v88
	v_add_f32_e32 v14, v14, v89
	v_add_f32_e32 v15, v15, v90
	v_add_f32_e32 v0, v0, v91
	v_add_f32_e32 v14, v14, v92
	v_add_f32_e32 v15, v15, v93
	v_add_f32_e32 v0, v0, v94
	v_add_f32_e32 v14, v14, v95
	v_cvt_pk_bf16_f32 v220, v88, v89
	v_cvt_pk_bf16_f32 v221, v90, v91
	v_cvt_pk_bf16_f32 v222, v92, v93
	v_cvt_pk_bf16_f32 v223, v94, v95
	v_add_f32_e32 v0, v0, v14
	v_add_f32_e32 v154, v154, v15
	v_add_f32_e32 v154, v154, v0
	s_mov_b32 s100, s28
	s_branch .LBB0_363
.Lq2_first:
	s_nop 10
	v_max3_f32 v0, v80, v81, v82
	v_max3_f32 v2, v83, v84, v85
	v_max3_f32 v3, v86, v87, v88
	v_max3_f32 v4, v89, v90, v91
	v_max3_f32 v0, v0, v92, v93
	v_max3_f32 v2, v2, v94, v95
	v_max3_f32 v3, v3, v96, v97
	v_max3_f32 v4, v4, v98, v99
	v_max3_f32 v0, v0, v100, v101
	v_max3_f32 v2, v2, v102, v103
	v_max3_f32 v3, v3, v104, v105
	v_max3_f32 v4, v4, v106, v107
	v_max3_f32 v0, v0, v108, v109
	v_max3_f32 v2, v2, v110, v111
	v_max3_f32 v0, v0, v3, v4
	v_max_f32_e32 v0, v0, v2
	v_mul_f32_e32 v0, 0x3e38aa3b, v0
	v_mov_b32_e32 v2, v0
	s_nop 1
	v_permlane32_swap_b32_e32 v0, v2
	v_max_f32_e32 v0, v0, v2
	v_add_f32_e32 v2, 0x41000000, v150
	v_cmp_gt_f32_e32 vcc, v0, v2
	s_cbranch_vccz .Lq2_fexp
	v_max_f32_e32 v0, v0, v0
	v_max_f32_e32 v2, v150, v150
	v_max_f32_e32 v2, v2, v0
	v_sub_f32_e32 v0, v150, v2
	v_exp_f32_e32 v0, v0
	v_mov_b32_e32 v150, v2
	v_pk_mul_f32 v[30:31], v[30:31], v[0:1] op_sel_hi:[1,0]
	v_pk_mul_f32 v[28:29], v[28:29], v[0:1] op_sel_hi:[1,0]
	v_pk_mul_f32 v[26:27], v[26:27], v[0:1] op_sel_hi:[1,0]
	v_pk_mul_f32 v[24:25], v[24:25], v[0:1] op_sel_hi:[1,0]
	v_pk_mul_f32 v[22:23], v[22:23], v[0:1] op_sel_hi:[1,0]
	v_pk_mul_f32 v[20:21], v[20:21], v[0:1] op_sel_hi:[1,0]
	v_pk_mul_f32 v[18:19], v[18:19], v[0:1] op_sel_hi:[1,0]
	v_pk_mul_f32 v[16:17], v[16:17], v[0:1] op_sel_hi:[1,0]
	v_pk_mul_f32 v[46:47], v[46:47], v[0:1] op_sel_hi:[1,0]
	v_pk_mul_f32 v[44:45], v[44:45], v[0:1] op_sel_hi:[1,0]
	v_pk_mul_f32 v[42:43], v[42:43], v[0:1] op_sel_hi:[1,0]
	v_pk_mul_f32 v[40:41], v[40:41], v[0:1] op_sel_hi:[1,0]
	v_pk_mul_f32 v[38:39], v[38:39], v[0:1] op_sel_hi:[1,0]
	v_pk_mul_f32 v[36:37], v[36:37], v[0:1] op_sel_hi:[1,0]
	v_pk_mul_f32 v[34:35], v[34:35], v[0:1] op_sel_hi:[1,0]
	v_pk_mul_f32 v[32:33], v[32:33], v[0:1] op_sel_hi:[1,0]
	v_pk_mul_f32 v[62:63], v[62:63], v[0:1] op_sel_hi:[1,0]
	v_pk_mul_f32 v[60:61], v[60:61], v[0:1] op_sel_hi:[1,0]
	v_pk_mul_f32 v[58:59], v[58:59], v[0:1] op_sel_hi:[1,0]
	v_pk_mul_f32 v[56:57], v[56:57], v[0:1] op_sel_hi:[1,0]
	v_pk_mul_f32 v[54:55], v[54:55], v[0:1] op_sel_hi:[1,0]
	v_pk_mul_f32 v[52:53], v[52:53], v[0:1] op_sel_hi:[1,0]
	v_pk_mul_f32 v[50:51], v[50:51], v[0:1] op_sel_hi:[1,0]
	v_pk_mul_f32 v[48:49], v[48:49], v[0:1] op_sel_hi:[1,0]
	v_pk_mul_f32 v[78:79], v[78:79], v[0:1] op_sel_hi:[1,0]
	v_pk_mul_f32 v[76:77], v[76:77], v[0:1] op_sel_hi:[1,0]
	v_pk_mul_f32 v[74:75], v[74:75], v[0:1] op_sel_hi:[1,0]
	v_pk_mul_f32 v[72:73], v[72:73], v[0:1] op_sel_hi:[1,0]
	v_pk_mul_f32 v[70:71], v[70:71], v[0:1] op_sel_hi:[1,0]
	v_pk_mul_f32 v[68:69], v[68:69], v[0:1] op_sel_hi:[1,0]
	v_pk_mul_f32 v[66:67], v[66:67], v[0:1] op_sel_hi:[1,0]
	v_pk_mul_f32 v[64:65], v[64:65], v[0:1] op_sel_hi:[1,0]
	v_mul_f32_e32 v154, v154, v0
.Lq2_fexp:
	v_fma_f32 v96, v96, s43, -v150
	v_exp_f32_e32 v96, v96
	v_fma_f32 v97, v97, s43, -v150
	v_exp_f32_e32 v97, v97
	v_fma_f32 v98, v98, s43, -v150
	v_exp_f32_e32 v98, v98
	v_fma_f32 v99, v99, s43, -v150
	v_exp_f32_e32 v99, v99
	v_fma_f32 v100, v100, s43, -v150
	v_exp_f32_e32 v100, v100
	v_fma_f32 v101, v101, s43, -v150
	v_exp_f32_e32 v101, v101
	v_fma_f32 v102, v102, s43, -v150
	v_exp_f32_e32 v102, v102
	v_fma_f32 v103, v103, s43, -v150
	v_exp_f32_e32 v103, v103
	v_add_f32_e32 v0, v96, v97
	v_add_f32_e32 v14, v98, v99
	v_add_f32_e32 v15, v100, v101
	v_add_f32_e32 v0, v0, v102
	v_add_f32_e32 v14, v14, v103
	v_cvt_pk_bf16_f32 v200, v96, v97
	v_cvt_pk_bf16_f32 v201, v98, v99
	v_cvt_pk_bf16_f32 v202, v100, v101
	v_cvt_pk_bf16_f32 v203, v102, v103
	v_fma_f32 v104, v104, s43, -v150
	v_exp_f32_e32 v104, v104
	v_fma_f32 v105, v105, s43, -v150
	v_exp_f32_e32 v105, v105
	v_fma_f32 v106, v106, s43, -v150
	v_exp_f32_e32 v106, v106
	v_fma_f32 v107, v107, s43, -v150
	v_exp_f32_e32 v107, v107
	v_fma_f32 v108, v108, s43, -v150
	v_exp_f32_e32 v108, v108
	v_fma_f32 v109, v109, s43, -v150
	v_exp_f32_e32 v109, v109
	v_fma_f32 v110, v110, s43, -v150
	v_exp_f32_e32 v110, v110
	v_fma_f32 v111, v111, s43, -v150
	v_exp_f32_e32 v111, v111
	v_add_f32_e32 v0, v0, v104
	v_add_f32_e32 v14, v14, v105
	v_add_f32_e32 v15, v15, v106
	v_add_f32_e32 v0, v0, v107
	v_add_f32_e32 v14, v14, v108
	v_add_f32_e32 v15, v15, v109
	v_add_f32_e32 v0, v0, v110
	v_add_f32_e32 v14, v14, v111
	v_cvt_pk_bf16_f32 v204, v104, v105
	v_cvt_pk_bf16_f32 v205, v106, v107
	v_cvt_pk_bf16_f32 v206, v108, v109
	v_cvt_pk_bf16_f32 v207, v110, v111
	v_fma_f32 v80, v80, s43, -v150
	v_exp_f32_e32 v80, v80
	v_fma_f32 v81, v81, s43, -v150
	v_exp_f32_e32 v81, v81
	v_fma_f32 v82, v82, s43, -v150
	v_exp_f32_e32 v82, v82
	v_fma_f32 v83, v83, s43, -v150
	v_exp_f32_e32 v83, v83
	v_fma_f32 v84, v84, s43, -v150
	v_exp_f32_e32 v84, v84
	v_fma_f32 v85, v85, s43, -v150
	v_exp_f32_e32 v85, v85
	v_fma_f32 v86, v86, s43, -v150
	v_exp_f32_e32 v86, v86
	v_fma_f32 v87, v87, s43, -v150
	v_exp_f32_e32 v87, v87
	v_add_f32_e32 v0, v0, v80
	v_add_f32_e32 v14, v14, v81
	v_add_f32_e32 v15, v15, v82
	v_add_f32_e32 v0, v0, v83
	v_add_f32_e32 v14, v14, v84
	v_add_f32_e32 v15, v15, v85
	v_add_f32_e32 v0, v0, v86
	v_add_f32_e32 v14, v14, v87
	v_cvt_pk_bf16_f32 v208, v80, v81
	v_cvt_pk_bf16_f32 v209, v82, v83
	v_cvt_pk_bf16_f32 v210, v84, v85
	v_cvt_pk_bf16_f32 v211, v86, v87
	v_fma_f32 v88, v88, s43, -v150
	v_exp_f32_e32 v88, v88
	v_fma_f32 v89, v89, s43, -v150
	v_exp_f32_e32 v89, v89
	v_fma_f32 v90, v90, s43, -v150
	v_exp_f32_e32 v90, v90
	v_fma_f32 v91, v91, s43, -v150
	v_exp_f32_e32 v91, v91
	v_fma_f32 v92, v92, s43, -v150
	v_exp_f32_e32 v92, v92
	v_fma_f32 v93, v93, s43, -v150
	v_exp_f32_e32 v93, v93
	v_fma_f32 v94, v94, s43, -v150
	v_exp_f32_e32 v94, v94
	v_fma_f32 v95, v95, s43, -v150
	v_exp_f32_e32 v95, v95
	v_add_f32_e32 v0, v0, v88
	v_add_f32_e32 v14, v14, v89
	v_add_f32_e32 v15, v15, v90
	v_add_f32_e32 v0, v0, v91
	v_add_f32_e32 v14, v14, v92
	v_add_f32_e32 v15, v15, v93
	v_add_f32_e32 v0, v0, v94
	v_add_f32_e32 v14, v14, v95
	v_cvt_pk_bf16_f32 v220, v88, v89
	v_cvt_pk_bf16_f32 v221, v90, v91
	v_cvt_pk_bf16_f32 v222, v92, v93
	v_cvt_pk_bf16_f32 v223, v94, v95
	v_add_f32_e32 v0, v0, v14
	v_add_f32_e32 v154, v154, v15
	v_add_f32_e32 v154, v154, v0
	s_mov_b32 s99, 1
	s_mov_b32 s100, s28
	s_branch .LBB0_363
.Lq2_exit:
	s_cmp_eq_u32 s99, 0
	s_cbranch_scc1 .LBB0_341
	v_add3_u32 v248, s100, v199, v187
	v_add3_u32 v249, s100, v199, v190
	v_add3_u32 v250, s100, v199, v191
	v_add3_u32 v251, s100, v199, v192
	ds_read_b64_tr_b16 v[2:3], v248 offset:8192
	ds_read_b64_tr_b16 v[4:5], v248 offset:10240
	ds_read_b64_tr_b16 v[6:7], v249 offset:8192
	ds_read_b64_tr_b16 v[8:9], v249 offset:10240
	ds_read_b64_tr_b16 v[10:11], v250 offset:8192
	ds_read_b64_tr_b16 v[12:13], v250 offset:10240
	ds_read_b64_tr_b16 v[244:245], v251 offset:8192
	ds_read_b64_tr_b16 v[246:247], v251 offset:10240
	s_waitcnt lgkmcnt(6)
	v_mfma_f32_32x32x16_bf16 v[16:31], v[2:5], v[200:203], v[16:31]
	ds_read_b64_tr_b16 v[156:157], v248 offset:12288
	ds_read_b64_tr_b16 v[158:159], v248 offset:14336
	ds_read_b64_tr_b16 v[160:161], v249 offset:12288
	ds_read_b64_tr_b16 v[162:163], v249 offset:14336
	ds_read_b64_tr_b16 v[252:253], v250 offset:12288
	ds_read_b64_tr_b16 v[254:255], v250 offset:14336
	ds_read_b64_tr_b16 v[216:217], v251 offset:12288
	ds_read_b64_tr_b16 v[218:219], v251 offset:14336
	s_waitcnt lgkmcnt(12)
	v_mfma_f32_32x32x16_bf16 v[32:47], v[6:9], v[200:203], v[32:47]
	s_waitcnt lgkmcnt(10)
	v_mfma_f32_32x32x16_bf16 v[48:63], v[10:13], v[200:203], v[48:63]
	s_waitcnt lgkmcnt(8)
	v_mfma_f32_32x32x16_bf16 v[64:79], v[244:247], v[200:203], v[64:79]
	s_waitcnt lgkmcnt(6)
	v_mfma_f32_32x32x16_bf16 v[16:31], v[156:159], v[204:207], v[16:31]
	ds_read_b64_tr_b16 v[2:3], v248 offset:16384
	ds_read_b64_tr_b16 v[4:5], v248 offset:18432
	ds_read_b64_tr_b16 v[6:7], v249 offset:16384
	ds_read_b64_tr_b16 v[8:9], v249 offset:18432
	ds_read_b64_tr_b16 v[10:11], v250 offset:16384
	ds_read_b64_tr_b16 v[12:13], v250 offset:18432
	ds_read_b64_tr_b16 v[244:245], v251 offset:16384
	ds_read_b64_tr_b16 v[246:247], v251 offset:18432
	s_waitcnt lgkmcnt(12)
	v_mfma_f32_32x32x16_bf16 v[32:47], v[160:163], v[204:207], v[32:47]
	s_waitcnt lgkmcnt(10)
	v_mfma_f32_32x32x16_bf16 v[48:63], v[252:255], v[204:207], v[48:63]
	s_waitcnt lgkmcnt(8)
	v_mfma_f32_32x32x16_bf16 v[64:79], v[216:219], v[204:207], v[64:79]
	s_waitcnt lgkmcnt(6)
	v_mfma_f32_32x32x16_bf16 v[16:31], v[2:5], v[208:211], v[16:31]
	ds_read_b64_tr_b16 v[156:157], v248 offset:20480
	ds_read_b64_tr_b16 v[158:159], v248 offset:22528
	ds_read_b64_tr_b16 v[160:161], v249 offset:20480
	ds_read_b64_tr_b16 v[162:163], v249 offset:22528
	ds_read_b64_tr_b16 v[252:253], v250 offset:20480
	ds_read_b64_tr_b16 v[254:255], v250 offset:22528
	ds_read_b64_tr_b16 v[216:217], v251 offset:20480
	ds_read_b64_tr_b16 v[218:219], v251 offset:22528
	s_waitcnt lgkmcnt(12)
	v_mfma_f32_32x32x16_bf16 v[32:47], v[6:9], v[208:211], v[32:47]
	s_waitcnt lgkmcnt(10)
	v_mfma_f32_32x32x16_bf16 v[48:63], v[10:13], v[208:211], v[48:63]
	s_waitcnt lgkmcnt(8)
	v_mfma_f32_32x32x16_bf16 v[64:79], v[244:247], v[208:211], v[64:79]
	s_waitcnt lgkmcnt(6)
	v_mfma_f32_32x32x16_bf16 v[16:31], v[156:159], v[220:223], v[16:31]
	s_waitcnt lgkmcnt(4)
	v_mfma_f32_32x32x16_bf16 v[32:47], v[160:163], v[220:223], v[32:47]
	s_waitcnt lgkmcnt(2)
	v_mfma_f32_32x32x16_bf16 v[48:63], v[252:255], v[220:223], v[48:63]
	s_waitcnt lgkmcnt(0)
	v_mfma_f32_32x32x16_bf16 v[64:79], v[216:219], v[220:223], v[64:79]
	s_mov_b32 s99, 0
	s_branch .LBB0_341
